# more de-serialised load chains: ret state-output loop, kv K staging (both instances)
# speedup vs baseline: 1.0422x; 1.0059x over previous
.LBB0_344:
	s_and_b64 s[40:41], s[36:37], exec
	s_cselect_b32 s3, s28, s38
	v_cvt_f32_i32_e32 v20, s3
	s_ashr_i32 s3, s2, 31
	s_lshl_b64 s[40:41], s[2:3], 14
	v_lshl_add_u64 v[22:23], v[18:19], 0, s[40:41]
	v_add_co_u32_e32 v24, vcc, s93, v22
	s_nop 1
	v_addc_co_u32_e32 v25, vcc, 0, v23, vcc
	v_add_co_u32_e32 v28, vcc, s31, v22
	s_nop 1
	v_addc_co_u32_e32 v29, vcc, 0, v23, vcc
	global_load_dword v128, v[22:23], off
	global_load_dword v129, v[22:23], off offset:1024
	global_load_dword v130, v[22:23], off offset:2048
	global_load_dword v131, v[22:23], off offset:3072
	v_add_co_u32_e32 v22, vcc, s63, v22
	s_nop 1
	v_addc_co_u32_e32 v23, vcc, 0, v23, vcc
	global_load_dword v132, v[24:25], off
	global_load_dword v133, v[24:25], off offset:1024
	global_load_dword v134, v[24:25], off offset:2048
	global_load_dword v135, v[24:25], off offset:3072
	global_load_dword v136, v[28:29], off
	global_load_dword v137, v[28:29], off offset:1024
	global_load_dword v138, v[28:29], off offset:2048
	global_load_dword v139, v[28:29], off offset:3072
	global_load_dword v140, v[22:23], off
	global_load_dword v141, v[22:23], off offset:1024
	global_load_dword v142, v[22:23], off offset:2048
	global_load_dword v143, v[22:23], off offset:3072
	v_mul_f32_e32 v20, v71, v20
	v_mul_f32_e32 v20, 0x3fb8aa3b, v20
	v_exp_f32_e32 v20, v20
	s_add_i32 s38, s38, 1
	s_add_i32 s28, s28, -1
	s_add_i32 s2, s2, 8
	s_cmp_eq_u32 s28, -1
	s_waitcnt vmcnt(0)
	v_pk_fma_f32 v[16:17], v[128:129], v[20:21], v[16:17] op_sel_hi:[1,0,1]
	v_pk_fma_f32 v[14:15], v[130:131], v[20:21], v[14:15] op_sel_hi:[1,0,1]
	v_pk_fma_f32 v[12:13], v[20:21], v[132:133], v[12:13] op_sel_hi:[0,1,1]
	v_pk_fma_f32 v[10:11], v[20:21], v[134:135], v[10:11] op_sel_hi:[0,1,1]
	v_pk_fma_f32 v[8:9], v[20:21], v[136:137], v[8:9] op_sel_hi:[0,1,1]
	v_pk_fma_f32 v[6:7], v[20:21], v[138:139], v[6:7] op_sel_hi:[0,1,1]
	v_pk_fma_f32 v[4:5], v[20:21], v[140:141], v[4:5] op_sel_hi:[0,1,1]
	v_pk_fma_f32 v[2:3], v[20:21], v[142:143], v[2:3] op_sel_hi:[0,1,1]
	s_cbranch_scc0 .LBB0_344
	s_and_b32 s2, s29, 0x1ffffffe
	v_readlane_b32 s28, v255, 36
	s_add_i32 s2, s2, s28
	s_lshl_b32 s2, s2, 3
	s_add_i32 s2, s2, s46
	s_or_b32 s2, s2, s57
	s_ashr_i32 s3, s2, 31
	s_lshl_b64 s[2:3], s[2:3], 14
	v_readlane_b32 s28, v254, 54
	s_add_u32 s2, s28, s2
	v_readlane_b32 s28, v254, 55
	s_addc_u32 s3, s28, s3
	v_lshl_add_u64 v[18:19], v[0:1], 2, s[2:3]
	global_store_dword v[18:19], v16, off
	global_store_dword v[18:19], v17, off offset:1024
	global_store_dword v[18:19], v14, off offset:2048
	global_store_dword v[18:19], v15, off offset:3072
	v_add_co_u32_e32 v14, vcc, s93, v18
	v_readlane_b32 s29, v255, 37
	s_nop 0
	v_addc_co_u32_e32 v15, vcc, 0, v19, vcc
	v_add_co_u32_e32 v16, vcc, s31, v18
	s_nop 1
	v_addc_co_u32_e32 v17, vcc, 0, v19, vcc
	global_store_dword v[16:17], v12, off offset:-4096
	global_store_dword v[14:15], v13, off offset:1024
	global_store_dword v[14:15], v10, off offset:2048
	global_store_dword v[14:15], v11, off offset:3072
	global_store_dword v[16:17], v8, off
	global_store_dword v[16:17], v9, off offset:1024
	global_store_dword v[16:17], v6, off offset:2048
	global_store_dword v[16:17], v7, off offset:3072
	v_add_co_u32_e32 v6, vcc, 0x3000, v18
	s_nop 1
	v_addc_co_u32_e32 v7, vcc, 0, v19, vcc
	global_store_dword v[6:7], v4, off
	global_store_dword v[6:7], v5, off offset:1024
	global_store_dword v[6:7], v2, off offset:2048
	global_store_dword v[6:7], v3, off offset:3072

.LBB0_425:
	v_add_u32_e32 v48, s0, v35
	v_add_u32_e32 v49, s0, v34
	v_max_i32_e32 v41, 0, v48
	v_min_i32_e32 v42, s40, v49
	v_sub_u32_e32 v41, v42, v41
	v_cvt_f32_i32_e32 v41, v41
	v_add_u32_e32 v50, s69, v38
	v_add_u32_e32 v52, s69, v37
	v_add_u32_e32 v53, s69, v36
	v_div_scale_f32 v42, s[28:29], v41, v41, v40
	v_rcp_f32_e32 v43, v42
	s_add_i32 s0, s0, 8
	v_add_u32_e32 v51, s69, v39
	v_add_u32_e32 v36, 0x2000, v36
	v_fma_f32 v44, -v42, v43, 1.0
	v_fmac_f32_e32 v43, v44, v43
	v_div_scale_f32 v44, vcc, v40, v41, v40
	v_mul_f32_e32 v45, v44, v43
	v_fma_f32 v46, -v42, v45, v44
	v_fmac_f32_e32 v45, v46, v43
	v_fma_f32 v42, -v42, v45, v44
	v_div_fmas_f32 v42, v42, v43, v45
	v_div_fixup_f32 v41, v42, v41, v40
	ds_read2st64_b32 v[42:43], v50 offset1:4
	ds_read2st64_b32 v[44:45], v52 offset1:4
	ds_read2st64_b32 v[46:47], v53 offset1:4
	v_add_u32_e32 v37, 0x2000, v37
	v_add_u32_e32 v38, 0x2000, v38
	s_waitcnt lgkmcnt(2)
	v_sub_f32_e32 v41, v41, v42
	v_cvt_pk_bf16_f32 v41, v41, s0
	ds_write_b16 v51, v41
	s_waitcnt lgkmcnt(1)
	v_sub_f32_e32 v41, v44, v46
	v_add_f32_e32 v40, v40, v41
	v_add_u32_e32 v41, 1, v48
	v_add_u32_e32 v42, 1, v49
	v_max_i32_e32 v41, 0, v41
	v_min_i32_e32 v42, s40, v42
	v_sub_u32_e32 v41, v42, v41
	v_cvt_f32_i32_e32 v41, v41
	v_add_u32_e32 v39, 0x1080, v39
	s_cmp_lg_u32 s0, 32
	v_div_scale_f32 v42, s[28:29], v41, v41, v40
	v_rcp_f32_e32 v44, v42
	s_nop 0
	v_fma_f32 v46, -v42, v44, 1.0
	v_fmac_f32_e32 v44, v46, v44
	v_div_scale_f32 v46, vcc, v40, v41, v40
	v_mul_f32_e32 v54, v46, v44
	v_fma_f32 v55, -v42, v54, v46
	v_fmac_f32_e32 v54, v55, v44
	v_fma_f32 v42, -v42, v54, v46
	v_div_fmas_f32 v42, v42, v44, v54
	v_div_fixup_f32 v41, v42, v41, v40
	v_sub_f32_e32 v41, v41, v43
	v_cvt_pk_bf16_f32 v41, v41, s0
	ds_write_b16 v51, v41 offset:528
	v_sub_f32_e32 v41, v45, v47
	v_add_f32_e32 v46, v40, v41
	v_add_u32_e32 v40, 2, v48
	v_add_u32_e32 v41, 2, v49
	v_max_i32_e32 v40, 0, v40
	v_min_i32_e32 v41, s40, v41
	v_sub_u32_e32 v40, v41, v40
	v_cvt_f32_i32_e32 v40, v40
	v_div_scale_f32 v41, s[28:29], v40, v40, v46
	v_rcp_f32_e32 v42, v41
	s_nop 0
	v_fma_f32 v43, -v41, v42, 1.0
	v_fmac_f32_e32 v42, v43, v42
	v_div_scale_f32 v43, vcc, v46, v40, v46
	v_mul_f32_e32 v44, v43, v42
	v_fma_f32 v45, -v41, v44, v43
	v_fmac_f32_e32 v44, v45, v42
	v_fma_f32 v41, -v41, v44, v43
	v_div_fmas_f32 v41, v41, v42, v44
	v_div_fixup_f32 v42, v41, v40, v46
	ds_read2st64_b32 v[40:41], v50 offset0:8 offset1:12
	s_waitcnt lgkmcnt(0)
	v_sub_f32_e32 v40, v42, v40
	v_cvt_pk_bf16_f32 v40, v40, s0
	ds_write_b16 v51, v40 offset:1056
	ds_read2st64_b32 v[42:43], v52 offset0:8 offset1:12
	ds_read2st64_b32 v[44:45], v53 offset0:8 offset1:12
	s_waitcnt lgkmcnt(0)
	v_sub_f32_e32 v40, v42, v44
	v_add_u32_e32 v42, 3, v48
	v_add_u32_e32 v44, 3, v49
	v_max_i32_e32 v42, 0, v42
	v_min_i32_e32 v44, s40, v44
	v_sub_u32_e32 v42, v44, v42
	v_cvt_f32_i32_e32 v42, v42
	v_add_f32_e32 v40, v46, v40
	v_div_scale_f32 v44, s[28:29], v42, v42, v40
	v_rcp_f32_e32 v46, v44
	s_nop 0
	v_fma_f32 v47, -v44, v46, 1.0
	v_fmac_f32_e32 v46, v47, v46
	v_div_scale_f32 v47, vcc, v40, v42, v40
	v_mul_f32_e32 v54, v47, v46
	v_fma_f32 v55, -v44, v54, v47
	v_fmac_f32_e32 v54, v55, v46
	v_fma_f32 v44, -v44, v54, v47
	v_div_fmas_f32 v44, v44, v46, v54
	v_div_fixup_f32 v42, v44, v42, v40
	v_sub_f32_e32 v41, v42, v41
	v_cvt_pk_bf16_f32 v41, v41, s0
	ds_write_b16 v51, v41 offset:1584
	v_sub_f32_e32 v41, v43, v45
	v_add_f32_e32 v46, v40, v41
	v_add_u32_e32 v40, 4, v48
	v_add_u32_e32 v41, 4, v49
	v_max_i32_e32 v40, 0, v40
	v_min_i32_e32 v41, s40, v41
	v_sub_u32_e32 v40, v41, v40
	v_cvt_f32_i32_e32 v40, v40
	v_div_scale_f32 v41, s[28:29], v40, v40, v46
	v_rcp_f32_e32 v42, v41
	s_nop 0
	v_fma_f32 v43, -v41, v42, 1.0
	v_fmac_f32_e32 v42, v43, v42
	v_div_scale_f32 v43, vcc, v46, v40, v46
	v_mul_f32_e32 v44, v43, v42
	v_fma_f32 v45, -v41, v44, v43
	v_fmac_f32_e32 v44, v45, v42
	v_fma_f32 v41, -v41, v44, v43
	v_div_fmas_f32 v41, v41, v42, v44
	v_div_fixup_f32 v42, v41, v40, v46
	ds_read2st64_b32 v[40:41], v50 offset0:16 offset1:20
	s_waitcnt lgkmcnt(0)
	v_sub_f32_e32 v40, v42, v40
	v_cvt_pk_bf16_f32 v40, v40, s0
	ds_write_b16 v51, v40 offset:2112
	ds_read2st64_b32 v[42:43], v52 offset0:16 offset1:20
	ds_read2st64_b32 v[44:45], v53 offset0:16 offset1:20
	s_waitcnt lgkmcnt(0)
	v_sub_f32_e32 v40, v42, v44
	v_add_u32_e32 v42, 5, v48
	v_add_u32_e32 v44, 5, v49
	v_max_i32_e32 v42, 0, v42
	v_min_i32_e32 v44, s40, v44
	v_sub_u32_e32 v42, v44, v42
	v_cvt_f32_i32_e32 v42, v42
	v_add_f32_e32 v40, v46, v40
	v_div_scale_f32 v44, s[28:29], v42, v42, v40
	v_rcp_f32_e32 v46, v44
	s_nop 0
	v_fma_f32 v47, -v44, v46, 1.0
	v_fmac_f32_e32 v46, v47, v46
	v_div_scale_f32 v47, vcc, v40, v42, v40
	v_mul_f32_e32 v54, v47, v46
	v_fma_f32 v55, -v44, v54, v47
	v_fmac_f32_e32 v54, v55, v46
	v_fma_f32 v44, -v44, v54, v47
	v_div_fmas_f32 v44, v44, v46, v54
	v_div_fixup_f32 v42, v44, v42, v40
	v_sub_f32_e32 v41, v42, v41
	v_cvt_pk_bf16_f32 v41, v41, s0
	ds_write_b16 v51, v41 offset:2640
	v_sub_f32_e32 v41, v43, v45
	v_add_f32_e32 v46, v40, v41
	v_add_u32_e32 v40, 6, v48
	v_add_u32_e32 v41, 6, v49
	v_max_i32_e32 v40, 0, v40
	v_min_i32_e32 v41, s40, v41
	v_sub_u32_e32 v40, v41, v40
	v_cvt_f32_i32_e32 v40, v40
	v_div_scale_f32 v41, s[28:29], v40, v40, v46
	v_rcp_f32_e32 v42, v41
	s_nop 0
	v_fma_f32 v43, -v41, v42, 1.0
	v_fmac_f32_e32 v42, v43, v42
	v_div_scale_f32 v43, vcc, v46, v40, v46
	v_mul_f32_e32 v44, v43, v42
	v_fma_f32 v45, -v41, v44, v43
	v_fmac_f32_e32 v44, v45, v42
	v_fma_f32 v41, -v41, v44, v43
	v_div_fmas_f32 v41, v41, v42, v44
	v_div_fixup_f32 v42, v41, v40, v46
	ds_read2st64_b32 v[40:41], v50 offset0:24 offset1:28
	s_waitcnt lgkmcnt(0)
	v_sub_f32_e32 v40, v42, v40
	v_cvt_pk_bf16_f32 v40, v40, s0
	ds_write_b16 v51, v40 offset:3168
	ds_read2st64_b32 v[42:43], v52 offset0:24 offset1:28
	ds_read2st64_b32 v[44:45], v53 offset0:24 offset1:28
	s_waitcnt lgkmcnt(0)
	v_sub_f32_e32 v40, v42, v44
	v_add_u32_e32 v42, 7, v48
	v_add_u32_e32 v44, 7, v49
	v_max_i32_e32 v42, 0, v42
	v_min_i32_e32 v44, s40, v44
	v_sub_u32_e32 v42, v44, v42
	v_cvt_f32_i32_e32 v42, v42
	v_add_f32_e32 v40, v46, v40
	v_div_scale_f32 v44, s[28:29], v42, v42, v40
	v_rcp_f32_e32 v46, v44
	s_nop 0
	v_fma_f32 v47, -v44, v46, 1.0
	v_fmac_f32_e32 v46, v47, v46
	v_div_scale_f32 v47, vcc, v40, v42, v40
	v_mul_f32_e32 v48, v47, v46
	v_fma_f32 v49, -v44, v48, v47
	v_fmac_f32_e32 v48, v49, v46
	v_fma_f32 v44, -v44, v48, v47
	v_div_fmas_f32 v44, v44, v46, v48
	v_div_fixup_f32 v42, v44, v42, v40
	v_sub_f32_e32 v41, v42, v41
	v_cvt_pk_bf16_f32 v41, v41, s0
	ds_write_b16 v51, v41 offset:3696
	v_sub_f32_e32 v41, v43, v45
	v_add_f32_e32 v40, v40, v41
	s_cbranch_scc1 .LBB0_425
	v_and_b32_e32 v33, 0xffffff80, v33
	v_add_u32_e32 v33, s69, v33
	v_mul_u32_u24_e32 v34, 0x210, v87
	s_waitcnt lgkmcnt(0)
	s_barrier
	v_add3_u32 v33, v33, v200, v34
	ds_read_b128 v[34:37], v33 offset:49152
	ds_read_b128 v[38:41], v33 offset:49216
	ds_read_b128 v[54:57], v33 offset:57600
	ds_read_b128 v[58:61], v33 offset:57664
	s_waitcnt vmcnt(11) lgkmcnt(3)
	v_mfma_f32_16x16x32_bf16 v[42:45], v[34:37], v[20:23], 0
	v_lshl_or_b32 v64, v32, 2, s3
	v_and_b32_e32 v62, 0xffffffcf, v82
	v_ashrrev_i32_e32 v63, 31, v62
	s_waitcnt vmcnt(7) lgkmcnt(2)
	v_mfma_f32_16x16x32_bf16 v[42:45], v[38:41], v[4:7], v[42:45]
	v_lshlrev_b64 v[62:63], 1, v[62:63]
	v_ashrrev_i32_e32 v65, 31, v64
	s_addk_i32 s2, 0x100
	s_waitcnt lgkmcnt(1)
	v_mfma_f32_16x16x32_bf16 v[20:23], v[54:57], v[20:23], 0
	s_ashr_i32 s29, s2, 3
	s_waitcnt vmcnt(3)
	s_nop 0
	v_mul_f32_e32 v32, v86, v42
	v_cvt_pk_bf16_f32 v42, v32, s0
	v_mfma_f32_16x16x32_bf16 v[46:49], v[34:37], v[16:19], 0
	v_lshlrev_b64 v[32:33], 11, v[64:65]
	v_lshl_add_u64 v[66:67], s[22:23], 0, v[32:33]
	v_mul_f32_e32 v32, v86, v43
	v_mfma_f32_16x16x32_bf16 v[16:19], v[54:57], v[16:19], 0
	v_cvt_pk_bf16_f32 v65, v32, s0
	v_or_b32_e32 v32, 1, v64
	v_ashrrev_i32_e32 v33, 31, v32
	s_waitcnt lgkmcnt(0)
	v_mfma_f32_16x16x32_bf16 v[4:7], v[58:61], v[4:7], v[20:23]
	v_lshl_add_u64 v[68:69], v[66:67], 0, v[62:63]
	v_lshlrev_b64 v[32:33], 11, v[32:33]
	global_store_short v[68:69], v42, off offset:1024
	v_mul_f32_e32 v20, v86, v45
	v_cvt_pk_bf16_f32 v22, v20, s0
	v_or_b32_e32 v20, 3, v64
	v_ashrrev_i32_e32 v21, 31, v20
	v_mfma_f32_16x16x32_bf16 v[46:49], v[38:41], v[8:11], v[46:49]
	v_mul_f32_e32 v4, v86, v4
	v_cvt_pk_bf16_f32 v4, v4, s0
	v_lshl_add_u64 v[42:43], s[22:23], 0, v[32:33]
	v_mfma_f32_16x16x32_bf16 v[8:11], v[58:61], v[8:11], v[16:19]
	v_mul_f32_e32 v32, v86, v44
	v_cvt_pk_bf16_f32 v44, v32, s0
	v_or_b32_e32 v32, 2, v64
	v_lshlrev_b64 v[16:17], 11, v[20:21]
	v_or_b32_e32 v20, 16, v64
	v_ashrrev_i32_e32 v21, 31, v20
	v_mfma_f32_16x16x32_bf16 v[50:53], v[34:37], v[24:27], 0
	v_lshl_add_u64 v[16:17], s[22:23], 0, v[16:17]
	v_lshlrev_b64 v[20:21], 11, v[20:21]
	v_lshl_add_u64 v[18:19], v[16:17], 0, v[62:63]
	v_mfma_f32_16x16x32_bf16 v[24:27], v[54:57], v[24:27], 0
	v_lshl_add_u64 v[20:21], s[22:23], 0, v[20:21]
	global_store_short v[18:19], v22, off offset:1024
	v_lshl_add_u64 v[22:23], v[20:21], 0, v[62:63]
	global_store_short v[22:23], v4, off offset:1024
	v_mul_f32_e32 v4, v86, v5
	v_mfma_f32_16x16x32_bf16 v[50:53], v[38:41], v[0:3], v[50:53]
	v_ashrrev_i32_e32 v33, 31, v32
	v_mul_f32_e32 v6, v86, v6
	s_waitcnt vmcnt(5)
	v_mul_f32_e32 v8, v85, v8
	v_mfma_f32_16x16x32_bf16 v[0:3], v[58:61], v[0:3], v[24:27]
	v_cvt_pk_bf16_f32 v6, v6, s0
	v_cvt_pk_bf16_f32 v8, v8, s0
	global_store_short v[22:23], v8, off offset:1056
	v_cvt_pk_bf16_f32 v26, v4, s0
	v_or_b32_e32 v4, 17, v64
	v_ashrrev_i32_e32 v5, 31, v4
	v_lshlrev_b64 v[4:5], 11, v[4:5]
	v_lshl_add_u64 v[4:5], s[22:23], 0, v[4:5]
	v_lshl_add_u64 v[24:25], v[4:5], 0, v[62:63]
	v_mfma_f32_16x16x32_bf16 v[34:37], v[34:37], v[28:31], 0
	global_store_short v[24:25], v26, off offset:1024
	v_or_b32_e32 v26, 18, v64
	v_ashrrev_i32_e32 v27, 31, v26
	v_mfma_f32_16x16x32_bf16 v[28:31], v[54:57], v[28:31], 0
	v_lshlrev_b64 v[26:27], 11, v[26:27]
	v_lshl_add_u64 v[26:27], s[22:23], 0, v[26:27]
	v_lshlrev_b64 v[56:57], 11, v[32:33]
	v_mfma_f32_16x16x32_bf16 v[32:35], v[38:41], v[12:15], v[34:37]
	v_mul_f32_e32 v8, v85, v9
	v_cvt_pk_bf16_f32 v8, v8, s0
	global_store_short v[24:25], v8, off offset:1056
	v_mfma_f32_16x16x32_bf16 v[12:15], v[58:61], v[12:15], v[28:31]
	v_mul_f32_e32 v8, v85, v10
	v_cvt_pk_bf16_f32 v8, v8, s0
	s_waitcnt vmcnt(7)
	v_mul_f32_e32 v0, v84, v0
	v_lshl_add_u64 v[28:29], v[26:27], 0, v[62:63]
	global_store_short v[28:29], v6, off offset:1024
	v_mul_f32_e32 v6, v86, v7
	v_cvt_pk_bf16_f32 v40, v6, s0
	v_or_b32_e32 v6, 19, v64
	v_ashrrev_i32_e32 v7, 31, v6
	v_lshlrev_b64 v[6:7], 11, v[6:7]
	v_lshl_add_u64 v[6:7], s[22:23], 0, v[6:7]
	global_store_short v[28:29], v8, off offset:1056
	v_mul_f32_e32 v8, v85, v11
	v_cvt_pk_bf16_f32 v0, v0, s0
	v_lshl_add_u64 v[30:31], v[6:7], 0, v[62:63]
	v_cvt_pk_bf16_f32 v8, v8, s0
	global_store_short v[22:23], v0, off offset:1088
	v_mul_f32_e32 v0, v84, v1
	global_store_short v[30:31], v8, off offset:1056
	v_mul_f32_e32 v8, v84, v50
	v_cvt_pk_bf16_f32 v0, v0, s0
	global_store_short v[30:31], v40, off offset:1024
	v_mul_f32_e32 v40, v85, v46
	v_cvt_pk_bf16_f32 v8, v8, s0
	global_store_short v[24:25], v0, off offset:1088
	v_mul_f32_e32 v0, v84, v2
	v_cvt_pk_bf16_f32 v40, v40, s0
	global_store_short v[68:69], v8, off offset:1088
	v_mul_f32_e32 v8, v84, v51
	v_cvt_pk_bf16_f32 v0, v0, s0
	v_lshl_add_u64 v[54:55], v[42:43], 0, v[62:63]
	global_store_short v[68:69], v40, off offset:1056
	v_mul_f32_e32 v40, v85, v47
	v_cvt_pk_bf16_f32 v8, v8, s0
	global_store_short v[28:29], v0, off offset:1088
	v_mul_f32_e32 v0, v84, v3
	v_lshl_add_u64 v[36:37], s[22:23], 0, v[56:57]
	v_cvt_pk_bf16_f32 v40, v40, s0
	global_store_short v[54:55], v8, off offset:1088
	v_mul_f32_e32 v8, v84, v52
	v_cvt_pk_bf16_f32 v0, v0, s0
	v_lshl_add_u64 v[38:39], v[36:37], 0, v[62:63]
	global_store_short v[54:55], v40, off offset:1056
	v_mul_f32_e32 v40, v85, v48
	v_cvt_pk_bf16_f32 v8, v8, s0
	global_store_short v[30:31], v0, off offset:1088
	v_or_b32_e32 v0, 48, v82
	v_cvt_pk_bf16_f32 v40, v40, s0
	global_store_short v[38:39], v8, off offset:1088
	v_mul_f32_e32 v8, v84, v53
	v_ashrrev_i32_e32 v1, 31, v0
	global_store_short v[38:39], v40, off offset:1056
	v_mul_f32_e32 v40, v85, v49
	v_cvt_pk_bf16_f32 v8, v8, s0
	s_waitcnt vmcnt(20)
	v_mul_f32_e32 v2, v83, v32
	v_lshlrev_b64 v[0:1], 1, v[0:1]
	v_cvt_pk_bf16_f32 v40, v40, s0
	global_store_short v[18:19], v8, off offset:1088
	v_cvt_pk_bf16_f32 v8, v2, s0
	v_lshl_add_u64 v[2:3], v[66:67], 0, v[0:1]
	global_store_short v[54:55], v65, off offset:1024
	global_store_short v[38:39], v44, off offset:1024
	global_store_short v[18:19], v40, off offset:1056
	global_store_short v[2:3], v8, off offset:1024
	v_mul_f32_e32 v2, v83, v33
	v_cvt_pk_bf16_f32 v8, v2, s0
	v_lshl_add_u64 v[2:3], v[42:43], 0, v[0:1]
	global_store_short v[2:3], v8, off offset:1024
	v_mul_f32_e32 v2, v83, v34
	v_cvt_pk_bf16_f32 v8, v2, s0
	v_lshl_add_u64 v[2:3], v[36:37], 0, v[0:1]
	global_store_short v[2:3], v8, off offset:1024
	v_mul_f32_e32 v2, v83, v35
	v_cvt_pk_bf16_f32 v8, v2, s0
	v_lshl_add_u64 v[2:3], v[16:17], 0, v[0:1]
	global_store_short v[2:3], v8, off offset:1024
	v_mul_f32_e32 v2, v83, v12
	v_cvt_pk_bf16_f32 v8, v2, s0
	v_lshl_add_u64 v[2:3], v[20:21], 0, v[0:1]
	global_store_short v[2:3], v8, off offset:1024
	v_mul_f32_e32 v2, v83, v13
	v_cvt_pk_bf16_f32 v8, v2, s0
	v_lshl_add_u64 v[2:3], v[4:5], 0, v[0:1]
	global_store_short v[2:3], v8, off offset:1024
	v_mul_f32_e32 v2, v83, v14
	v_cvt_pk_bf16_f32 v4, v2, s0
	v_lshl_add_u64 v[2:3], v[26:27], 0, v[0:1]
	s_bfe_u32 s3, s2, 0x20001
	s_lshl_b32 s28, s29, 7
	global_store_short v[2:3], v4, off offset:1024
	v_mul_f32_e32 v2, v83, v15
	s_cmp_gt_i32 s29, 31
	v_cvt_pk_bf16_f32 v2, v2, s0
	s_cselect_b64 s[0:1], -1, 0
	s_or_b32 s38, s3, s79
	s_ashr_i32 s39, s38, 31
	v_readlane_b32 s40, v253, 3
	s_lshl_b64 s[38:39], s[38:39], 2
	v_readlane_b32 s48, v253, 11
	v_readlane_b32 s49, v253, 12
	s_add_u32 s38, s48, s38
	v_lshl_add_u64 v[0:1], v[6:7], 0, v[0:1]
	v_readlane_b32 s41, v253, 4
	s_addc_u32 s39, s49, s39
	s_mul_i32 s40, s29, 0xb0000
	global_store_short v[0:1], v2, off offset:1024
	v_mov_b32_e32 v38, v229
	v_readlane_b32 s42, v253, 5
	s_mul_hi_i32 s41, s28, 0x1600
	s_add_u32 s40, s20, s40
	v_mov_b32_e32 v22, v229
	s_waitcnt lgkmcnt(0)
	s_barrier
	s_addc_u32 s41, s21, s41
	s_lshl_b32 s42, s3, 7
	global_load_dword v41, v201, s[38:39]
	s_add_u32 s40, s40, s42
	v_lshlrev_b32_e32 v0, 2, v22
	v_and_b32_e32 v23, 60, v0
	s_addc_u32 s41, s41, 0
	v_lshlrev_b32_e32 v200, 1, v23
	v_lshl_add_u64 v[0:1], s[40:41], 0, v[200:201]
	s_mov_b64 s[38:39], 0x1200
	v_lshl_add_u64 v[0:1], v[0:1], 0, s[38:39]
	v_ashrrev_i32_e32 v2, 4, v22
	v_mad_i64_i32 v[2:3], s[38:39], v2, s92, v[0:1]
	global_load_dwordx2 v[2:3], v[2:3], off
	v_add_u32_e32 v24, 0x100, v22
	v_ashrrev_i32_e32 v4, 4, v24
	v_mad_i64_i32 v[4:5], s[38:39], v4, s92, v[0:1]
	global_load_dwordx2 v[4:5], v[4:5], off
	v_add_u32_e32 v25, 0x200, v22
	v_ashrrev_i32_e32 v6, 4, v25
	v_mad_i64_i32 v[6:7], s[38:39], v6, s92, v[0:1]
	global_load_dwordx2 v[6:7], v[6:7], off
	v_add_u32_e32 v26, 0x300, v22
	v_ashrrev_i32_e32 v8, 4, v26
	v_mad_i64_i32 v[8:9], s[38:39], v8, s92, v[0:1]
	global_load_dwordx2 v[8:9], v[8:9], off
	v_add_u32_e32 v27, 0x400, v22
	v_ashrrev_i32_e32 v10, 4, v27
	v_mad_i64_i32 v[10:11], s[38:39], v10, s92, v[0:1]
	global_load_dwordx2 v[10:11], v[10:11], off
	v_add_u32_e32 v28, 0x500, v22
	s_lshl_b32 s40, s80, 1
	v_ashrrev_i32_e32 v12, 4, v28
	s_or_b32 s38, s42, s40
	v_mad_i64_i32 v[12:13], s[40:41], v12, s92, v[0:1]
	s_add_u32 s38, s20, s38
	global_load_dwordx2 v[12:13], v[12:13], off
	v_add_u32_e32 v29, 0x600, v22
	v_add_u32_e32 v30, 0x700, v22
	v_bfe_u32 v31, v38, 2, 1
	s_addc_u32 s39, s21, 0
	v_ashrrev_i32_e32 v14, 4, v29
	v_ashrrev_i32_e32 v16, 4, v30
	v_lshlrev_b32_e32 v200, 6, v31
	v_lshlrev_b32_e32 v39, 3, v38
	v_mad_i64_i32 v[14:15], s[40:41], v14, s92, v[0:1]
	v_mad_i64_i32 v[0:1], s[40:41], v16, s92, v[0:1]
	v_lshl_add_u64 v[16:17], s[38:39], 0, v[200:201]
	v_and_b32_e32 v200, 24, v39
	v_ashrrev_i32_e32 v40, 3, v38
	global_load_dwordx2 v[14:15], v[14:15], off
	v_lshl_add_u64 v[16:17], v[16:17], 0, v[200:201]
	v_add_u32_e32 v18, s28, v40
	v_mad_i64_i32 v[18:19], s[38:39], v18, s92, v[16:17]
	global_load_dwordx2 v[0:1], v[0:1], off
	s_nop 0
	global_load_dwordx2 v[20:21], v[18:19], off
	s_nop 0
	global_load_dwordx2 v[18:19], v[18:19], off offset:32
	s_cmp_lt_i32 s29, 32
	v_mov_b32_e32 v32, s69
	s_movk_i32 s29, 0x110
	v_ashrrev_i32_e32 v22, 3, v22
	v_mad_u32_u24 v23, v23, s29, v32
	v_and_b32_e32 v22, -2, v22
	v_add_u32_e32 v22, v23, v22
	s_waitcnt vmcnt(9)
	ds_write_b16 v22, v2 offset:17408
	ds_write_b16_d16_hi v22, v2 offset:17680
	ds_write_b16 v22, v3 offset:17952
	ds_write_b16_d16_hi v22, v3 offset:18224
	v_ashrrev_i32_e32 v2, 3, v24
	v_and_b32_e32 v2, -2, v2
	v_add_u32_e32 v2, v23, v2
	s_waitcnt vmcnt(8)
	ds_write_b16 v2, v4 offset:17408
	ds_write_b16_d16_hi v2, v4 offset:17680
	ds_write_b16 v2, v5 offset:17952
	ds_write_b16_d16_hi v2, v5 offset:18224
	v_ashrrev_i32_e32 v2, 3, v25
	v_and_b32_e32 v2, -2, v2
	v_add_u32_e32 v2, v23, v2
	s_waitcnt vmcnt(7)
	ds_write_b16 v2, v6 offset:17408
	ds_write_b16_d16_hi v2, v6 offset:17680
	ds_write_b16 v2, v7 offset:17952
	ds_write_b16_d16_hi v2, v7 offset:18224
	v_ashrrev_i32_e32 v2, 3, v26
	v_and_b32_e32 v2, -2, v2
	v_add_u32_e32 v2, v23, v2
	s_waitcnt vmcnt(6)
	ds_write_b16 v2, v8 offset:17408
	ds_write_b16_d16_hi v2, v8 offset:17680
	ds_write_b16 v2, v9 offset:17952
	ds_write_b16_d16_hi v2, v9 offset:18224
	v_ashrrev_i32_e32 v2, 3, v27
	v_and_b32_e32 v2, -2, v2
	v_add_u32_e32 v2, v23, v2
	s_waitcnt vmcnt(5)
	ds_write_b16 v2, v10 offset:17408
	ds_write_b16_d16_hi v2, v10 offset:17680
	ds_write_b16 v2, v11 offset:17952
	ds_write_b16_d16_hi v2, v11 offset:18224
	v_ashrrev_i32_e32 v2, 3, v28
	v_and_b32_e32 v2, -2, v2
	v_add_u32_e32 v2, v23, v2
	s_waitcnt vmcnt(4)
	ds_write_b16 v2, v12 offset:17408
	ds_write_b16_d16_hi v2, v12 offset:17680
	ds_write_b16 v2, v13 offset:17952
	ds_write_b16_d16_hi v2, v13 offset:18224
	v_ashrrev_i32_e32 v2, 3, v29
	v_and_b32_e32 v2, -2, v2
	s_cselect_b64 s[40:41], -1, 0
	v_add_u32_e32 v2, v23, v2
	s_waitcnt vmcnt(3)
	ds_write_b16 v2, v14 offset:17408
	ds_write_b16_d16_hi v2, v14 offset:17680
	ds_write_b16 v2, v15 offset:17952
	ds_write_b16_d16_hi v2, v15 offset:18224
	v_ashrrev_i32_e32 v2, 3, v30
	s_and_b64 vcc, s[40:41], exec
	s_mov_b32 s29, 0x80000380
	v_and_b32_e32 v2, -2, v2
	s_cselect_b32 s29, 0x80, s29
	v_add_u32_e32 v2, v23, v2
	v_cmp_eq_u32_e64 s[38:39], 0, v31
	s_and_b32 s29, s29, s28
	s_waitcnt vmcnt(1)
	v_lshlrev_b32_e32 v12, 16, v20
	v_and_b32_e32 v13, 0xffff0000, v20
	v_lshlrev_b32_e32 v15, 16, v21
	s_waitcnt vmcnt(0)
	v_lshlrev_b32_e32 v8, 16, v18
	v_and_b32_e32 v9, 0xffff0000, v18
	v_lshlrev_b32_e32 v14, 16, v19
	v_and_b32_e32 v11, 0xffff0000, v19
	v_and_b32_e32 v10, 0xffff0000, v21
	s_mov_b64 s[40:41], -1
	v_readlane_b32 s43, v253, 6
	v_readlane_b32 s44, v253, 7
	v_readlane_b32 s45, v253, 8
	v_readlane_b32 s46, v253, 9
	v_readlane_b32 s47, v253, 10
	v_readlane_b32 s50, v253, 13
	v_readlane_b32 s51, v253, 14
	v_readlane_b32 s52, v253, 15
	v_readlane_b32 s53, v253, 16
	v_readlane_b32 s54, v253, 17
	v_readlane_b32 s55, v253, 18
	ds_write_b16 v2, v0 offset:17408
	ds_write_b16_d16_hi v2, v0 offset:17680
	ds_write_b16 v2, v1 offset:17952
	ds_write_b16_d16_hi v2, v1 offset:18224
	v_add_u32_e32 v54, 0x100, v38
	v_ashrrev_i32_e32 v42, 3, v54
	v_add_u32_e32 v46, s28, v42
	v_mad_i64_i32 v[48:49], vcc, v46, s92, v[16:17]
	global_load_dwordx2 v[60:61], v[48:49], off
	global_load_dwordx2 v[62:63], v[48:49], off offset:32
	v_add_u32_e32 v55, 0x200, v38
	v_ashrrev_i32_e32 v43, 3, v55
	v_add_u32_e32 v46, s28, v43
	v_mad_i64_i32 v[48:49], vcc, v46, s92, v[16:17]
	global_load_dwordx2 v[64:65], v[48:49], off
	global_load_dwordx2 v[66:67], v[48:49], off offset:32
	v_add_u32_e32 v56, 0x300, v38
	v_ashrrev_i32_e32 v44, 3, v56
	v_add_u32_e32 v46, s28, v44
	v_mad_i64_i32 v[48:49], vcc, v46, s92, v[16:17]
	global_load_dwordx2 v[68:69], v[48:49], off
	global_load_dwordx2 v[70:71], v[48:49], off offset:32
	s_and_b64 vcc, exec, s[0:1]
	s_cbranch_vccz .Lkv_norot_a
	v_add_u32_e32 v32, s29, v40
	v_ashrrev_i32_e32 v32, 6, v32
	v_bfe_u32 v33, v38, 3, 6
	v_cndmask_b32_e64 v32, v33, v32, s[38:39]
	v_lshl_or_b32 v32, v32, 5, v200
	v_lshlrev_b32_e32 v50, 2, v32
	global_load_dwordx4 v[72:75], v50, s[12:13]
	global_load_dwordx4 v[76:79], v50, s[12:13] offset:16
	v_add_u32_e32 v32, s29, v42
	v_ashrrev_i32_e32 v32, 6, v32
	v_bfe_u32 v33, v54, 3, 6
	v_cndmask_b32_e64 v32, v33, v32, s[38:39]
	v_lshl_or_b32 v32, v32, 5, v200
	v_lshlrev_b32_e32 v51, 2, v32
	global_load_dwordx4 v[80:83], v51, s[12:13]
	global_load_dwordx4 v[84:87], v51, s[12:13] offset:16
	v_add_u32_e32 v32, s29, v43
	v_ashrrev_i32_e32 v32, 6, v32
	v_bfe_u32 v33, v55, 3, 6
	v_cndmask_b32_e64 v32, v33, v32, s[38:39]
	v_lshl_or_b32 v32, v32, 5, v200
	v_lshlrev_b32_e32 v52, 2, v32
	global_load_dwordx4 v[88:91], v52, s[12:13]
	global_load_dwordx4 v[92:95], v52, s[12:13] offset:16
	v_add_u32_e32 v32, s29, v44
	v_ashrrev_i32_e32 v32, 6, v32
	v_bfe_u32 v33, v56, 3, 6
	v_cndmask_b32_e64 v32, v33, v32, s[38:39]
	v_lshl_or_b32 v32, v32, 5, v200
	v_lshlrev_b32_e32 v53, 2, v32
	global_load_dwordx4 v[96:99], v53, s[12:13]
	global_load_dwordx4 v[100:103], v53, s[12:13] offset:16
	s_waitcnt vmcnt(0)
	v_mul_f32_e32 v34, v8, v73
	v_mul_f32_e32 v35, v12, v73
	v_fma_f32 v0, v12, v72, -v34
	v_fma_f32 v6, v8, v72, v35
	v_mul_f32_e32 v34, v9, v75
	v_mul_f32_e32 v35, v13, v75
	v_fma_f32 v1, v13, v74, -v34
	v_fma_f32 v7, v9, v74, v35
	v_mul_f32_e32 v34, v14, v77
	v_mul_f32_e32 v35, v15, v77
	v_fma_f32 v2, v15, v76, -v34
	v_fma_f32 v4, v14, v76, v35
	v_mul_f32_e32 v34, v11, v79
	v_mul_f32_e32 v35, v10, v79
	v_fma_f32 v3, v10, v78, -v34
	v_fma_f32 v5, v11, v78, v35
	v_lshlrev_b32_e32 v32, 16, v60
	v_lshlrev_b32_e32 v33, 16, v62
	v_mul_f32_e32 v34, v33, v81
	v_mul_f32_e32 v35, v32, v81
	v_fma_f32 v8, v32, v80, -v34
	v_fma_f32 v14, v33, v80, v35
	v_and_b32_e32 v32, 0xffff0000, v60
	v_and_b32_e32 v33, 0xffff0000, v62
	v_mul_f32_e32 v34, v33, v83
	v_mul_f32_e32 v35, v32, v83
	v_fma_f32 v9, v32, v82, -v34
	v_fma_f32 v15, v33, v82, v35
	v_lshlrev_b32_e32 v32, 16, v61
	v_lshlrev_b32_e32 v33, 16, v63
	v_mul_f32_e32 v34, v33, v85
	v_mul_f32_e32 v35, v32, v85
	v_fma_f32 v10, v32, v84, -v34
	v_fma_f32 v12, v33, v84, v35
	v_and_b32_e32 v32, 0xffff0000, v61
	v_and_b32_e32 v33, 0xffff0000, v63
	v_mul_f32_e32 v34, v33, v87
	v_mul_f32_e32 v35, v32, v87
	v_fma_f32 v11, v32, v86, -v34
	v_fma_f32 v13, v33, v86, v35
	v_lshlrev_b32_e32 v32, 16, v64
	v_lshlrev_b32_e32 v33, 16, v66
	v_mul_f32_e32 v34, v33, v89
	v_mul_f32_e32 v35, v32, v89
	v_fma_f32 v18, v32, v88, -v34
	v_fma_f32 v24, v33, v88, v35
	v_and_b32_e32 v32, 0xffff0000, v64
	v_and_b32_e32 v33, 0xffff0000, v66
	v_mul_f32_e32 v34, v33, v91
	v_mul_f32_e32 v35, v32, v91
	v_fma_f32 v19, v32, v90, -v34
	v_fma_f32 v25, v33, v90, v35
	v_lshlrev_b32_e32 v32, 16, v65
	v_lshlrev_b32_e32 v33, 16, v67
	v_mul_f32_e32 v34, v33, v93
	v_mul_f32_e32 v35, v32, v93
	v_fma_f32 v20, v32, v92, -v34
	v_fma_f32 v22, v33, v92, v35
	v_and_b32_e32 v32, 0xffff0000, v65
	v_and_b32_e32 v33, 0xffff0000, v67
	v_mul_f32_e32 v34, v33, v95
	v_mul_f32_e32 v35, v32, v95
	v_fma_f32 v21, v32, v94, -v34
	v_fma_f32 v23, v33, v94, v35
	v_lshlrev_b32_e32 v32, 16, v68
	v_lshlrev_b32_e32 v33, 16, v70
	v_mul_f32_e32 v34, v33, v97
	v_mul_f32_e32 v35, v32, v97
	v_fma_f32 v16, v32, v96, -v34
	v_fma_f32 v30, v33, v96, v35
	v_and_b32_e32 v32, 0xffff0000, v68
	v_and_b32_e32 v33, 0xffff0000, v70
	v_mul_f32_e32 v34, v33, v99
	v_mul_f32_e32 v35, v32, v99
	v_fma_f32 v17, v32, v98, -v34
	v_fma_f32 v31, v33, v98, v35
	v_lshlrev_b32_e32 v32, 16, v69
	v_lshlrev_b32_e32 v33, 16, v71
	v_mul_f32_e32 v34, v33, v101
	v_mul_f32_e32 v35, v32, v101
	v_fma_f32 v26, v32, v100, -v34
	v_fma_f32 v28, v33, v100, v35
	v_and_b32_e32 v32, 0xffff0000, v69
	v_and_b32_e32 v33, 0xffff0000, v71
	v_mul_f32_e32 v34, v33, v103
	v_mul_f32_e32 v35, v32, v103
	v_fma_f32 v27, v32, v102, -v34
	v_fma_f32 v29, v33, v102, v35
	s_branch .Lkv_done_a
.Lkv_norot_a:
	s_waitcnt vmcnt(0)
	v_mov_b32_e32 v0, v12
	v_mov_b32_e32 v6, v8
	v_mov_b32_e32 v1, v13
	v_mov_b32_e32 v7, v9
	v_mov_b32_e32 v2, v15
	v_mov_b32_e32 v4, v14
	v_mov_b32_e32 v3, v10
	v_mov_b32_e32 v5, v11
	v_lshlrev_b32_e32 v8, 16, v60
	v_lshlrev_b32_e32 v14, 16, v62
	v_and_b32_e32 v9, 0xffff0000, v60
	v_and_b32_e32 v15, 0xffff0000, v62
	v_lshlrev_b32_e32 v10, 16, v61
	v_lshlrev_b32_e32 v12, 16, v63
	v_and_b32_e32 v11, 0xffff0000, v61
	v_and_b32_e32 v13, 0xffff0000, v63
	v_lshlrev_b32_e32 v18, 16, v64
	v_lshlrev_b32_e32 v24, 16, v66
	v_and_b32_e32 v19, 0xffff0000, v64
	v_and_b32_e32 v25, 0xffff0000, v66
	v_lshlrev_b32_e32 v20, 16, v65
	v_lshlrev_b32_e32 v22, 16, v67
	v_and_b32_e32 v21, 0xffff0000, v65
	v_and_b32_e32 v23, 0xffff0000, v67
	v_lshlrev_b32_e32 v16, 16, v68
	v_lshlrev_b32_e32 v30, 16, v70
	v_and_b32_e32 v17, 0xffff0000, v68
	v_and_b32_e32 v31, 0xffff0000, v70
	v_lshlrev_b32_e32 v26, 16, v69
	v_lshlrev_b32_e32 v28, 16, v71
	v_and_b32_e32 v27, 0xffff0000, v69
	v_and_b32_e32 v29, 0xffff0000, v71
.Lkv_done_a:
.LBB0_442:
	v_mul_f32_e32 v32, 0xbfb8aa3b, v41
	v_rndne_f32_e32 v33, v32
	s_mov_b32 s0, 0xbfb8aa3b
	v_sub_f32_e32 v34, v32, v33
	v_fma_f32 v32, v41, s0, -v32
	v_fmac_f32_e32 v32, 0xb2a5705f, v41
	v_add_f32_e32 v32, v34, v32
	v_cvt_i32_f32_e32 v33, v33
	v_exp_f32_e32 v32, v32
	s_mov_b32 s0, 0x42ce8ed0
	v_cmp_nlt_f32_e32 vcc, s0, v41
	s_mov_b32 s0, 0xc2b17218
	v_ldexp_f32 v32, v32, v33
	v_cndmask_b32_e32 v32, 0, v32, vcc
	v_cmp_ngt_f32_e32 vcc, s0, v41
	s_mov_b32 s0, 0x3f2aaaab
	s_movk_i32 s28, 0x110
	v_cndmask_b32_e32 v34, v252, v32, vcc
	v_add_f32_e32 v35, 1.0, v34
	v_cvt_f64_f32_e32 v[32:33], v35
	v_frexp_exp_i32_f64_e32 v32, v[32:33]
	v_frexp_mant_f32_e32 v33, v35
	v_cmp_gt_f32_e32 vcc, s0, v33
	v_add_f32_e32 v46, -1.0, v35
	v_sub_f32_e32 v47, v34, v46
	v_subbrev_co_u32_e32 v32, vcc, 0, v32, vcc
	v_cvt_f32_i32_e32 v33, v32
	v_sub_u32_e32 v32, 0, v32
	v_ldexp_f32 v41, v35, v32
	v_sub_f32_e32 v35, v46, v35
	v_add_f32_e32 v35, 1.0, v35
	v_add_f32_e32 v46, 1.0, v41
	v_add_f32_e32 v35, v47, v35
	v_add_f32_e32 v47, -1.0, v46
	v_ldexp_f32 v32, v35, v32
	v_sub_f32_e32 v47, v41, v47
	v_add_f32_e32 v47, v32, v47
	v_add_f32_e32 v45, -1.0, v41
	v_add_f32_e32 v48, v46, v47
	v_add_f32_e32 v35, 1.0, v45
	v_rcp_f32_e32 v49, v48
	v_sub_f32_e32 v35, v41, v35
	v_add_f32_e32 v32, v32, v35
	v_add_f32_e32 v35, v45, v32
	v_mul_f32_e32 v41, v35, v49
	v_mul_f32_e32 v50, v48, v41
	v_sub_f32_e32 v46, v46, v48
	v_add_f32_e32 v46, v47, v46
	v_fma_f32 v47, v41, v48, -v50
	v_fmac_f32_e32 v47, v41, v46
	v_add_f32_e32 v51, v50, v47
	v_sub_f32_e32 v52, v35, v51
	v_sub_f32_e32 v45, v45, v35
	v_sub_f32_e32 v35, v35, v52
	v_sub_f32_e32 v50, v51, v50
	v_add_f32_e32 v32, v32, v45
	v_sub_f32_e32 v35, v35, v51
	v_sub_f32_e32 v47, v50, v47
	v_add_f32_e32 v32, v32, v35
	v_add_f32_e32 v32, v47, v32
	v_add_f32_e32 v35, v52, v32
	v_mul_f32_e32 v45, v49, v35
	v_mul_f32_e32 v50, v48, v45
	v_add_f32_e32 v47, v41, v45
	v_fma_f32 v48, v45, v48, -v50
	v_sub_f32_e32 v41, v47, v41
	v_fmac_f32_e32 v48, v45, v46
	v_sub_f32_e32 v41, v45, v41
	v_add_f32_e32 v45, v50, v48
	v_sub_f32_e32 v46, v35, v45
	v_sub_f32_e32 v50, v45, v50
	v_sub_f32_e32 v48, v50, v48
	v_sub_f32_e32 v50, v52, v35
	v_sub_f32_e32 v35, v35, v46
	v_add_f32_e32 v32, v32, v50
	v_sub_f32_e32 v35, v35, v45
	v_add_f32_e32 v32, v32, v35
	v_add_f32_e32 v32, v48, v32
	v_add_f32_e32 v32, v46, v32
	v_mul_f32_e32 v32, v49, v32
	v_add_f32_e32 v32, v41, v32
	v_add_f32_e32 v35, v47, v32
	v_mul_f32_e32 v45, v35, v35
	v_fmamk_f32 v48, v45, 0x3e9b6dac, v251
	v_mul_f32_e32 v46, v35, v45
	v_fmaak_f32 v45, v45, v48, 0x3f2aaada
	v_ldexp_f32 v41, v35, 1
	v_mul_f32_e32 v45, v46, v45
	v_add_f32_e32 v46, v41, v45
	v_sub_f32_e32 v35, v35, v47
	v_mul_f32_e32 v36, 0x3f317218, v33
	s_mov_b32 s0, 0x3f317218
	v_sub_f32_e32 v32, v32, v35
	v_sub_f32_e32 v35, v46, v41
	v_fma_f32 v37, v33, s0, -v36
	v_ldexp_f32 v32, v32, 1
	v_sub_f32_e32 v35, v45, v35
	v_fmac_f32_e32 v37, 0xb102e308, v33
	v_add_f32_e32 v32, v32, v35
	v_add_f32_e32 v33, v36, v37
	v_add_f32_e32 v35, v46, v32
	v_add_f32_e32 v41, v33, v35
	v_sub_f32_e32 v36, v33, v36
	v_sub_f32_e32 v36, v37, v36
	v_sub_f32_e32 v37, v35, v46
	v_sub_f32_e32 v45, v41, v33
	v_sub_f32_e32 v32, v32, v37
	v_sub_f32_e32 v35, v35, v45
	v_sub_f32_e32 v45, v41, v45
	v_add_f32_e32 v37, v36, v32
	v_sub_f32_e32 v33, v33, v45
	v_add_f32_e32 v33, v35, v33
	v_sub_f32_e32 v45, v37, v36
	v_add_f32_e32 v33, v37, v33
	v_sub_f32_e32 v37, v37, v45
	v_add_f32_e32 v35, v41, v33
	v_sub_f32_e32 v32, v32, v45
	v_sub_f32_e32 v36, v36, v37
	v_add_f32_e32 v32, v32, v36
	v_sub_f32_e32 v36, v35, v41
	v_sub_f32_e32 v33, v33, v36
	v_add_f32_e32 v32, v32, v33
	v_sub_u32_e32 v33, 0x7f, v40
	v_cndmask_b32_e64 v33, v40, v33, s[36:37]
	s_mov_b32 s0, 0x7f800000
	v_cvt_f32_i32_e32 v33, v33
	v_add_f32_e32 v32, v35, v32
	v_cmp_neq_f32_e32 vcc, s0, v34
	s_mov_b32 s0, 0x33800000
	v_mov_b32_e32 v35, s69
	v_cndmask_b32_e32 v32, v252, v32, vcc
	v_cmp_lt_f32_e64 vcc, |v34|, s0
	s_nop 1
	v_cndmask_b32_e32 v32, v32, v34, vcc
	v_mul_f32_e32 v33, v33, v32
	v_mul_f32_e32 v33, 0xbfb8aa3b, v33
	v_exp_f32_e32 v33, v33
	v_lshlrev_b32_e32 v34, 2, v38
	v_and_b32_e32 v34, 12, v34
	v_and_or_b32 v34, v39, 32, v34
	v_mul_f32_e32 v33, 0x3e000000, v33
	v_mad_u32_u24 v34, v34, s28, v35
	v_mul_f32_e32 v0, v33, v0
	v_cvt_pk_bf16_f32 v0, v0, s0
	v_lshl_add_u32 v35, v40, 1, v34
	ds_write_b16 v35, v0
	v_mul_f32_e32 v0, v33, v1
	v_cvt_pk_bf16_f32 v0, v0, s0
	ds_write_b16 v35, v0 offset:272
	v_mul_f32_e32 v0, v33, v2
	v_cvt_pk_bf16_f32 v0, v0, s0
	ds_write_b16 v35, v0 offset:544
	v_mul_f32_e32 v0, v33, v3
	v_cvt_pk_bf16_f32 v0, v0, s0
	ds_write_b16 v35, v0 offset:816
	v_mul_f32_e32 v0, v33, v6
	v_cvt_pk_bf16_f32 v0, v0, s0
	ds_write_b16 v35, v0 offset:4352
	v_mul_f32_e32 v0, v33, v7
	v_cvt_pk_bf16_f32 v0, v0, s0
	ds_write_b16 v35, v0 offset:4624
	v_sub_u32_e32 v0, 0x7f, v42
	v_cndmask_b32_e64 v0, v42, v0, s[36:37]
	v_cvt_f32_i32_e32 v0, v0
	v_mul_f32_e32 v1, v33, v4
	v_cvt_pk_bf16_f32 v1, v1, s0
	ds_write_b16 v35, v1 offset:4896
	v_mul_f32_e32 v0, v0, v32
	v_mul_f32_e32 v0, 0xbfb8aa3b, v0
	v_exp_f32_e32 v0, v0
	v_mul_f32_e32 v1, v33, v5
	v_cvt_pk_bf16_f32 v1, v1, s0
	ds_write_b16 v35, v1 offset:5168
	v_mul_f32_e32 v0, 0x3e000000, v0
	v_mul_f32_e32 v1, v0, v8
	v_cvt_pk_bf16_f32 v1, v1, s0
	v_lshl_add_u32 v2, v42, 1, v34
	ds_write_b16 v2, v1
	v_mul_f32_e32 v1, v0, v9
	v_cvt_pk_bf16_f32 v1, v1, s0
	ds_write_b16 v2, v1 offset:272
	v_mul_f32_e32 v1, v0, v10
	v_cvt_pk_bf16_f32 v1, v1, s0
	ds_write_b16 v2, v1 offset:544
	v_mul_f32_e32 v1, v0, v11
	v_cvt_pk_bf16_f32 v1, v1, s0
	ds_write_b16 v2, v1 offset:816
	v_mul_f32_e32 v1, v0, v14
	v_cvt_pk_bf16_f32 v1, v1, s0
	ds_write_b16 v2, v1 offset:4352
	v_mul_f32_e32 v1, v0, v15
	v_cvt_pk_bf16_f32 v1, v1, s0
	ds_write_b16 v2, v1 offset:4624
	v_sub_u32_e32 v1, 0x7f, v43
	v_cndmask_b32_e64 v1, v43, v1, s[36:37]
	v_cvt_f32_i32_e32 v1, v1
	v_mul_f32_e32 v3, v0, v12
	v_mul_f32_e32 v0, v0, v13
	v_cvt_pk_bf16_f32 v0, v0, s0
	v_mul_f32_e32 v1, v1, v32
	v_mul_f32_e32 v1, 0xbfb8aa3b, v1
	v_exp_f32_e32 v1, v1
	ds_write_b16 v2, v0 offset:5168
	v_cvt_pk_bf16_f32 v3, v3, s0
	ds_write_b16 v2, v3 offset:4896
	v_mul_f32_e32 v0, 0x3e000000, v1
	v_mul_f32_e32 v1, v0, v18
	v_cvt_pk_bf16_f32 v1, v1, s0
	v_lshl_add_u32 v2, v43, 1, v34
	ds_write_b16 v2, v1
	v_mul_f32_e32 v1, v0, v19
	v_cvt_pk_bf16_f32 v1, v1, s0
	ds_write_b16 v2, v1 offset:272
	v_mul_f32_e32 v1, v0, v20
	v_cvt_pk_bf16_f32 v1, v1, s0
	ds_write_b16 v2, v1 offset:544
	v_mul_f32_e32 v1, v0, v21
	v_cvt_pk_bf16_f32 v1, v1, s0
	ds_write_b16 v2, v1 offset:816
	v_mul_f32_e32 v1, v0, v24
	v_cvt_pk_bf16_f32 v1, v1, s0
	ds_write_b16 v2, v1 offset:4352
	v_mul_f32_e32 v1, v0, v25
	v_cvt_pk_bf16_f32 v1, v1, s0
	ds_write_b16 v2, v1 offset:4624
	v_sub_u32_e32 v1, 0x7f, v44
	v_cndmask_b32_e64 v1, v44, v1, s[36:37]
	v_cvt_f32_i32_e32 v1, v1
	v_mul_f32_e32 v3, v0, v22
	v_mul_f32_e32 v0, v0, v23
	v_cvt_pk_bf16_f32 v0, v0, s0
	v_mul_f32_e32 v1, v1, v32
	v_mul_f32_e32 v1, 0xbfb8aa3b, v1
	v_exp_f32_e32 v1, v1
	ds_write_b16 v2, v0 offset:5168
	v_cvt_pk_bf16_f32 v3, v3, s0
	ds_write_b16 v2, v3 offset:4896
	v_mul_f32_e32 v0, 0x3e000000, v1
	v_mul_f32_e32 v1, v0, v16
	v_cvt_pk_bf16_f32 v1, v1, s0
	v_lshl_add_u32 v2, v44, 1, v34
	ds_write_b16 v2, v1
	v_mul_f32_e32 v1, v0, v17
	v_cvt_pk_bf16_f32 v1, v1, s0
	ds_write_b16 v2, v1 offset:272
	v_mul_f32_e32 v1, v0, v26
	v_cvt_pk_bf16_f32 v1, v1, s0
	ds_write_b16 v2, v1 offset:544
	v_mul_f32_e32 v1, v0, v27
	v_cvt_pk_bf16_f32 v1, v1, s0
	ds_write_b16 v2, v1 offset:816
	v_mul_f32_e32 v1, v0, v30
	v_cvt_pk_bf16_f32 v1, v1, s0
	ds_write_b16 v2, v1 offset:4352
	v_mul_f32_e32 v1, v0, v31
	v_cvt_pk_bf16_f32 v1, v1, s0
	ds_write_b16 v2, v1 offset:4624
	v_mul_f32_e32 v1, v0, v28
	v_mul_f32_e32 v0, v0, v29
	v_cvt_pk_bf16_f32 v1, v1, s0
	v_cvt_pk_bf16_f32 v0, v0, s0
	v_bfe_u32 v30, v38, 4, 2
	v_ashrrev_i32_e32 v31, 2, v38
	ds_write_b16 v2, v1 offset:4896
	ds_write_b16 v2, v0 offset:5168
	v_bfi_b32 v0, -16, v31, v38
	v_lshl_add_u32 v4, v30, 4, s69
	s_waitcnt lgkmcnt(0)
	s_barrier
	v_mad_u64_u32 v[28:29], s[0:1], v0, s28, v[4:5]
	ds_read_b128 v[0:3], v28
	v_and_b32_e32 v29, 15, v38
	v_mad_u32_u24 v32, v29, s28, v4
	ds_read_b128 v[4:7], v32 offset:17408
	ds_read_b128 v[8:11], v32 offset:21760
	ds_read_b128 v[12:15], v32 offset:26112
	ds_read_b128 v[16:19], v32 offset:30464
	ds_read_b128 v[20:23], v28 offset:64
	s_waitcnt lgkmcnt(4)
	v_mfma_f32_16x16x32_bf16 v[4:7], v[0:3], v[4:7], 0
	s_and_b32 s0, s2, -8
	s_lshl_b32 s1, s3, 1
	s_or_b32 s0, s1, s0
	s_waitcnt lgkmcnt(3)
	v_mfma_f32_16x16x32_bf16 v[8:11], v[0:3], v[8:11], 0
	s_or_b32 s0, s0, s78
	s_ashr_i32 s1, s0, 31
	s_lshl_b64 s[0:1], s[0:1], 14
	s_waitcnt lgkmcnt(2)
	v_mfma_f32_16x16x32_bf16 v[12:15], v[0:3], v[12:15], 0
	s_add_u32 s0, s26, s0
	s_addc_u32 s1, s27, s1
	s_waitcnt lgkmcnt(1)
	v_mfma_f32_16x16x32_bf16 v[0:3], v[0:3], v[16:19], 0
	ds_read_b128 v[16:19], v32 offset:17472
	s_waitcnt lgkmcnt(0)
	v_mfma_f32_16x16x32_bf16 v[4:7], v[20:23], v[16:19], v[4:7]
	ds_read_b128 v[16:19], v32 offset:21824
	s_waitcnt lgkmcnt(0)
	v_mfma_f32_16x16x32_bf16 v[8:11], v[20:23], v[16:19], v[8:11]
	ds_read_b128 v[16:19], v32 offset:26176
	ds_read_b128 v[24:27], v32 offset:30528
	s_waitcnt lgkmcnt(1)
	v_mfma_f32_16x16x32_bf16 v[12:15], v[20:23], v[16:19], v[12:15]
	ds_read_b128 v[16:19], v28 offset:128
	s_waitcnt lgkmcnt(1)
	v_mfma_f32_16x16x32_bf16 v[0:3], v[20:23], v[24:27], v[0:3]
	ds_read_b128 v[20:23], v32 offset:17536
	s_waitcnt lgkmcnt(0)
	v_mfma_f32_16x16x32_bf16 v[4:7], v[16:19], v[20:23], v[4:7]
	ds_read_b128 v[20:23], v32 offset:21888
	s_waitcnt lgkmcnt(0)
	v_mfma_f32_16x16x32_bf16 v[8:11], v[16:19], v[20:23], v[8:11]
	ds_read_b128 v[20:23], v32 offset:26240
	ds_read_b128 v[24:27], v32 offset:30592
	s_waitcnt lgkmcnt(1)
	v_mfma_f32_16x16x32_bf16 v[12:15], v[16:19], v[20:23], v[12:15]
	ds_read_b128 v[20:23], v28 offset:192
	s_waitcnt lgkmcnt(1)
	v_mfma_f32_16x16x32_bf16 v[0:3], v[16:19], v[24:27], v[0:3]
	ds_read_b128 v[16:19], v32 offset:17600
	v_and_b32_e32 v28, -16, v31
	v_lshlrev_b32_e32 v28, 6, v28
	s_waitcnt lgkmcnt(0)
	v_mfma_f32_16x16x32_bf16 v[4:7], v[20:23], v[16:19], v[4:7]
	ds_read_b128 v[16:19], v32 offset:21952
	ds_read_b128 v[24:27], v32 offset:26304
	s_waitcnt lgkmcnt(1)
	v_mfma_f32_16x16x32_bf16 v[8:11], v[20:23], v[16:19], v[8:11]
	ds_read_b128 v[16:19], v32 offset:30656
	s_waitcnt lgkmcnt(1)
	v_mfma_f32_16x16x32_bf16 v[12:15], v[20:23], v[24:27], v[12:15]
	v_lshl_or_b32 v24, v30, 8, v28
	v_or_b32_e32 v26, v29, v24
	v_ashrrev_i32_e32 v25, 31, v24
	v_ashrrev_i32_e32 v27, 31, v26
	s_waitcnt lgkmcnt(0)
	v_mfma_f32_16x16x32_bf16 v[0:3], v[20:23], v[16:19], v[0:3]
	v_lshl_add_u64 v[16:17], v[26:27], 2, s[0:1]
	v_mov_b32_e32 v27, v25
	global_store_dword v[16:17], v4, off
	v_lshl_add_u64 v[16:17], v[26:27], 2, s[0:1]
	v_or_b32_e32 v24, 16, v26
	global_store_dword v[16:17], v5, off offset:256
	global_store_dword v[16:17], v6, off offset:512
	global_store_dword v[16:17], v7, off offset:768
	global_store_dword v[16:17], v8, off offset:64
	v_lshl_add_u64 v[4:5], v[24:25], 2, s[0:1]
	v_or_b32_e32 v24, 32, v26
	global_store_dword v[4:5], v9, off offset:256
	global_store_dword v[4:5], v10, off offset:512
	global_store_dword v[4:5], v11, off offset:768
	global_store_dword v[16:17], v12, off offset:128
	v_lshl_add_u64 v[4:5], v[24:25], 2, s[0:1]
	v_or_b32_e32 v24, 48, v26
	global_store_dword v[4:5], v13, off offset:256
	global_store_dword v[4:5], v14, off offset:512
	global_store_dword v[4:5], v15, off offset:768
	global_store_dword v[16:17], v0, off offset:192
	v_lshl_add_u64 v[4:5], v[24:25], 2, s[0:1]
	global_store_dword v[4:5], v1, off offset:256
	global_store_dword v[4:5], v2, off offset:512
	global_store_dword v[4:5], v3, off offset:768
	s_waitcnt lgkmcnt(0)
	s_barrier
	s_branch .LBB0_391

.LBB0_521:
	s_or_b64 exec, exec, s[0:1]
	s_waitcnt lgkmcnt(0)
	s_barrier
	v_lshl_add_u32 v40, v122, 2, s69
	ds_read2st64_b32 v[10:11], v40 offset1:4
	ds_read2st64_b32 v[14:15], v40 offset0:8 offset1:12
	ds_read2st64_b32 v[20:21], v40 offset0:16 offset1:20
	ds_read2st64_b32 v[12:13], v40 offset0:112 offset1:116
	ds_read2st64_b32 v[24:25], v40 offset0:24 offset1:28
	s_waitcnt lgkmcnt(4)
	v_fma_f32 v41, v108, v10, v75
	ds_read2st64_b32 v[28:29], v40 offset0:32 offset1:36
	ds_read2st64_b32 v[32:33], v40 offset0:40 offset1:44
	ds_read2st64_b32 v[36:37], v40 offset0:48 offset1:52
	ds_read2st64_b32 v[38:39], v40 offset0:56 offset1:60
	ds_read2st64_b32 v[34:35], v40 offset0:64 offset1:68
	ds_read2st64_b32 v[30:31], v40 offset0:72 offset1:76
	ds_read2st64_b32 v[26:27], v40 offset0:80 offset1:84
	ds_read2st64_b32 v[22:23], v40 offset0:88 offset1:92
	ds_read2st64_b32 v[18:19], v40 offset0:96 offset1:100
	ds_read2st64_b32 v[16:17], v40 offset0:104 offset1:108
	ds_read2st64_b32 v[8:9], v40 offset0:120 offset1:124
	v_fma_f32 v42, v108, v11, v75
	v_fmac_f32_e32 v41, v107, v11
	ds_read2st64_b32 v[10:11], v40 offset0:128 offset1:132
	s_waitcnt lgkmcnt(14)
	v_fma_f32 v43, v108, v14, v75
	v_fmac_f32_e32 v42, v107, v14
	v_fmac_f32_e32 v41, v106, v14
	v_fma_f32 v44, v108, v15, v75
	v_fma_f32 v45, v108, v20, v75
	v_fmac_f32_e32 v43, v107, v15
	v_fmac_f32_e32 v42, v106, v15
	v_fmac_f32_e32 v41, v103, v15
	ds_read2st64_b32 v[14:15], v40 offset0:136 offset1:140
	v_fma_f32 v46, v108, v21, v75
	s_waitcnt lgkmcnt(14)
	v_fma_f32 v69, v108, v12, v75
	v_fmac_f32_e32 v44, v107, v20
	v_fmac_f32_e32 v45, v107, v21
	v_fmac_f32_e32 v43, v106, v20
	v_fmac_f32_e32 v42, v103, v20
	v_fmac_f32_e32 v41, v101, v20
	s_waitcnt lgkmcnt(13)
	v_fma_f32 v47, v108, v24, v75
	v_fma_f32 v48, v108, v25, v75
	s_waitcnt lgkmcnt(12)
	v_fma_f32 v49, v108, v28, v75
	v_fma_f32 v50, v108, v29, v75
	s_waitcnt lgkmcnt(11)
	v_fma_f32 v51, v108, v32, v75
	v_fma_f32 v52, v108, v33, v75
	s_waitcnt lgkmcnt(10)
	v_fma_f32 v53, v108, v36, v75
	v_fma_f32 v54, v108, v37, v75
	s_waitcnt lgkmcnt(9)
	v_fma_f32 v55, v108, v38, v75
	v_fma_f32 v56, v108, v39, v75
	s_waitcnt lgkmcnt(8)
	v_fma_f32 v57, v108, v34, v75
	v_fma_f32 v58, v108, v35, v75
	s_waitcnt lgkmcnt(7)
	v_fma_f32 v59, v108, v30, v75
	v_fma_f32 v60, v108, v31, v75
	s_waitcnt lgkmcnt(6)
	v_fma_f32 v61, v108, v26, v75
	v_fma_f32 v62, v108, v27, v75
	s_waitcnt lgkmcnt(5)
	v_fma_f32 v63, v108, v22, v75
	v_fma_f32 v64, v108, v23, v75
	s_waitcnt lgkmcnt(4)
	v_fma_f32 v65, v108, v18, v75
	v_fma_f32 v66, v108, v19, v75
	s_waitcnt lgkmcnt(3)
	v_fma_f32 v67, v108, v16, v75
	v_fma_f32 v68, v108, v17, v75
	v_fma_f32 v70, v108, v13, v75
	s_waitcnt lgkmcnt(2)
	v_fma_f32 v71, v108, v8, v75
	v_fmac_f32_e32 v75, v108, v9
	v_fmac_f32_e32 v46, v107, v24
	v_fmac_f32_e32 v69, v107, v13
	v_fmac_f32_e32 v44, v106, v21
	v_fmac_f32_e32 v45, v106, v24
	v_fmac_f32_e32 v43, v103, v21
	v_fmac_f32_e32 v42, v101, v21
	v_fmac_f32_e32 v41, v100, v21
	ds_read2st64_b32 v[20:21], v40 offset0:144 offset1:148
	v_fmac_f32_e32 v47, v107, v25
	v_fmac_f32_e32 v48, v107, v28
	v_fmac_f32_e32 v49, v107, v29
	v_fmac_f32_e32 v50, v107, v32
	v_fmac_f32_e32 v51, v107, v33
	v_fmac_f32_e32 v52, v107, v36
	v_fmac_f32_e32 v53, v107, v37
	v_fmac_f32_e32 v54, v107, v38
	v_fmac_f32_e32 v55, v107, v39
	v_fmac_f32_e32 v56, v107, v34
	v_fmac_f32_e32 v57, v107, v35
	v_fmac_f32_e32 v58, v107, v30
	v_fmac_f32_e32 v59, v107, v31
	v_fmac_f32_e32 v60, v107, v26
	v_fmac_f32_e32 v61, v107, v27
	v_fmac_f32_e32 v62, v107, v22
	v_fmac_f32_e32 v63, v107, v23
	v_fmac_f32_e32 v64, v107, v18
	v_fmac_f32_e32 v65, v107, v19
	v_fmac_f32_e32 v66, v107, v16
	v_fmac_f32_e32 v67, v107, v17
	v_fmac_f32_e32 v68, v107, v12
	v_fmac_f32_e32 v70, v107, v8
	v_fmac_f32_e32 v71, v107, v9
	s_waitcnt lgkmcnt(2)
	v_fmac_f32_e32 v75, v107, v10
	v_fmac_f32_e32 v46, v106, v25
	v_fmac_f32_e32 v69, v106, v8
	v_fmac_f32_e32 v44, v103, v24
	v_fmac_f32_e32 v45, v103, v25
	v_fmac_f32_e32 v43, v101, v24
	v_fmac_f32_e32 v42, v100, v24
	v_fmac_f32_e32 v41, v99, v24
	v_fmac_f32_e32 v47, v106, v28
	v_fmac_f32_e32 v48, v106, v29
	v_fmac_f32_e32 v49, v106, v32
	v_fmac_f32_e32 v50, v106, v33
	v_fmac_f32_e32 v51, v106, v36
	v_fmac_f32_e32 v52, v106, v37
	v_fmac_f32_e32 v53, v106, v38
	v_fmac_f32_e32 v54, v106, v39
	v_fmac_f32_e32 v55, v106, v34
	v_fmac_f32_e32 v56, v106, v35
	v_fmac_f32_e32 v57, v106, v30
	v_fmac_f32_e32 v58, v106, v31
	v_fmac_f32_e32 v59, v106, v26
	v_fmac_f32_e32 v60, v106, v27
	v_fmac_f32_e32 v61, v106, v22
	v_fmac_f32_e32 v62, v106, v23
	v_fmac_f32_e32 v63, v106, v18
	v_fmac_f32_e32 v64, v106, v19
	v_fmac_f32_e32 v65, v106, v16
	v_fmac_f32_e32 v66, v106, v17
	v_fmac_f32_e32 v67, v106, v12
	v_fmac_f32_e32 v68, v106, v13
	v_fmac_f32_e32 v70, v106, v9
	v_fmac_f32_e32 v71, v106, v10
	v_fmac_f32_e32 v75, v106, v11
	v_fmac_f32_e32 v46, v103, v28
	v_fmac_f32_e32 v69, v103, v9
	v_fmac_f32_e32 v44, v101, v25
	v_fmac_f32_e32 v45, v101, v28
	v_fmac_f32_e32 v43, v100, v25
	v_fmac_f32_e32 v42, v99, v25
	v_fmac_f32_e32 v41, v98, v25
	ds_read2st64_b32 v[24:25], v40 offset0:152 offset1:156
	v_fmac_f32_e32 v47, v103, v29
	v_fmac_f32_e32 v48, v103, v32
	v_fmac_f32_e32 v49, v103, v33
	v_fmac_f32_e32 v50, v103, v36
	v_fmac_f32_e32 v51, v103, v37
	v_fmac_f32_e32 v52, v103, v38
	v_fmac_f32_e32 v53, v103, v39
	v_fmac_f32_e32 v54, v103, v34
	v_fmac_f32_e32 v55, v103, v35
	v_fmac_f32_e32 v56, v103, v30
	v_fmac_f32_e32 v57, v103, v31
	v_fmac_f32_e32 v58, v103, v26
	v_fmac_f32_e32 v59, v103, v27
	v_fmac_f32_e32 v60, v103, v22
	v_fmac_f32_e32 v61, v103, v23
	v_fmac_f32_e32 v62, v103, v18
	v_fmac_f32_e32 v63, v103, v19
	v_fmac_f32_e32 v64, v103, v16
	v_fmac_f32_e32 v65, v103, v17
	v_fmac_f32_e32 v66, v103, v12
	v_fmac_f32_e32 v67, v103, v13
	v_fmac_f32_e32 v68, v103, v8
	v_fmac_f32_e32 v70, v103, v10
	v_fmac_f32_e32 v71, v103, v11
	s_waitcnt lgkmcnt(2)
	v_fmac_f32_e32 v75, v103, v14
	v_fmac_f32_e32 v46, v101, v29
	v_fmac_f32_e32 v69, v101, v10
	v_fmac_f32_e32 v44, v100, v28
	v_fmac_f32_e32 v45, v100, v29
	v_fmac_f32_e32 v43, v99, v28
	v_fmac_f32_e32 v42, v98, v28
	v_fmac_f32_e32 v41, v97, v28
	v_fmac_f32_e32 v47, v101, v32
	v_fmac_f32_e32 v48, v101, v33
	v_fmac_f32_e32 v49, v101, v36
	v_fmac_f32_e32 v50, v101, v37
	v_fmac_f32_e32 v51, v101, v38
	v_fmac_f32_e32 v52, v101, v39
	v_fmac_f32_e32 v53, v101, v34
	v_fmac_f32_e32 v54, v101, v35
	v_fmac_f32_e32 v55, v101, v30
	v_fmac_f32_e32 v56, v101, v31
	v_fmac_f32_e32 v57, v101, v26
	v_fmac_f32_e32 v58, v101, v27
	v_fmac_f32_e32 v59, v101, v22
	v_fmac_f32_e32 v60, v101, v23
	v_fmac_f32_e32 v61, v101, v18
	v_fmac_f32_e32 v62, v101, v19
	v_fmac_f32_e32 v63, v101, v16
	v_fmac_f32_e32 v64, v101, v17
	v_fmac_f32_e32 v65, v101, v12
	v_fmac_f32_e32 v66, v101, v13
	v_fmac_f32_e32 v67, v101, v8
	v_fmac_f32_e32 v68, v101, v9
	v_fmac_f32_e32 v70, v101, v11
	v_fmac_f32_e32 v71, v101, v14
	v_fmac_f32_e32 v75, v101, v15
	v_fmac_f32_e32 v46, v100, v32
	v_fmac_f32_e32 v69, v100, v11
	v_fmac_f32_e32 v44, v99, v29
	v_fmac_f32_e32 v45, v99, v32
	v_fmac_f32_e32 v43, v98, v29
	v_fmac_f32_e32 v42, v97, v29
	v_fmac_f32_e32 v41, v96, v29
	ds_read2st64_b32 v[28:29], v40 offset0:160 offset1:164
	v_fmac_f32_e32 v47, v100, v33
	v_fmac_f32_e32 v48, v100, v36
	v_fmac_f32_e32 v49, v100, v37
	v_fmac_f32_e32 v50, v100, v38
	v_fmac_f32_e32 v51, v100, v39
	v_fmac_f32_e32 v52, v100, v34
	v_fmac_f32_e32 v53, v100, v35
	v_fmac_f32_e32 v54, v100, v30
	v_fmac_f32_e32 v55, v100, v31
	v_fmac_f32_e32 v56, v100, v26
	v_fmac_f32_e32 v57, v100, v27
	v_fmac_f32_e32 v58, v100, v22
	v_fmac_f32_e32 v59, v100, v23
	v_fmac_f32_e32 v60, v100, v18
	v_fmac_f32_e32 v61, v100, v19
	v_fmac_f32_e32 v62, v100, v16
	v_fmac_f32_e32 v63, v100, v17
	v_fmac_f32_e32 v64, v100, v12
	v_fmac_f32_e32 v65, v100, v13
	v_fmac_f32_e32 v66, v100, v8
	v_fmac_f32_e32 v67, v100, v9
	v_fmac_f32_e32 v68, v100, v10
	v_fmac_f32_e32 v70, v100, v14
	v_fmac_f32_e32 v71, v100, v15
	s_waitcnt lgkmcnt(2)
	v_fmac_f32_e32 v75, v100, v20
	v_fmac_f32_e32 v46, v99, v33
	v_fmac_f32_e32 v69, v99, v14
	v_fmac_f32_e32 v44, v98, v32
	v_fmac_f32_e32 v45, v98, v33
	v_fmac_f32_e32 v43, v97, v32
	v_fmac_f32_e32 v42, v96, v32
	v_fmac_f32_e32 v41, v95, v32
	v_fmac_f32_e32 v47, v99, v36
	v_fmac_f32_e32 v48, v99, v37
	v_fmac_f32_e32 v49, v99, v38
	v_fmac_f32_e32 v50, v99, v39
	v_fmac_f32_e32 v51, v99, v34
	v_fmac_f32_e32 v52, v99, v35
	v_fmac_f32_e32 v53, v99, v30
	v_fmac_f32_e32 v54, v99, v31
	v_fmac_f32_e32 v55, v99, v26
	v_fmac_f32_e32 v56, v99, v27
	v_fmac_f32_e32 v57, v99, v22
	v_fmac_f32_e32 v58, v99, v23
	v_fmac_f32_e32 v59, v99, v18
	v_fmac_f32_e32 v60, v99, v19
	v_fmac_f32_e32 v61, v99, v16
	v_fmac_f32_e32 v62, v99, v17
	v_fmac_f32_e32 v63, v99, v12
	v_fmac_f32_e32 v64, v99, v13
	v_fmac_f32_e32 v65, v99, v8
	v_fmac_f32_e32 v66, v99, v9
	v_fmac_f32_e32 v67, v99, v10
	v_fmac_f32_e32 v68, v99, v11
	v_fmac_f32_e32 v70, v99, v15
	v_fmac_f32_e32 v71, v99, v20
	v_fmac_f32_e32 v75, v99, v21
	v_fmac_f32_e32 v46, v98, v36
	v_fmac_f32_e32 v69, v98, v15
	v_fmac_f32_e32 v44, v97, v33
	v_fmac_f32_e32 v45, v97, v36
	v_fmac_f32_e32 v43, v96, v33
	v_fmac_f32_e32 v42, v95, v33
	v_fmac_f32_e32 v41, v94, v33
	ds_read2st64_b32 v[32:33], v40 offset0:168 offset1:172
	v_fmac_f32_e32 v47, v98, v37
	v_fmac_f32_e32 v48, v98, v38
	v_fmac_f32_e32 v49, v98, v39
	v_fmac_f32_e32 v50, v98, v34
	v_fmac_f32_e32 v51, v98, v35
	v_fmac_f32_e32 v52, v98, v30
	v_fmac_f32_e32 v53, v98, v31
	v_fmac_f32_e32 v54, v98, v26
	v_fmac_f32_e32 v55, v98, v27
	v_fmac_f32_e32 v56, v98, v22
	v_fmac_f32_e32 v57, v98, v23
	v_fmac_f32_e32 v58, v98, v18
	v_fmac_f32_e32 v59, v98, v19
	v_fmac_f32_e32 v60, v98, v16
	v_fmac_f32_e32 v61, v98, v17
	v_fmac_f32_e32 v62, v98, v12
	v_fmac_f32_e32 v63, v98, v13
	v_fmac_f32_e32 v64, v98, v8
	v_fmac_f32_e32 v65, v98, v9
	v_fmac_f32_e32 v66, v98, v10
	v_fmac_f32_e32 v67, v98, v11
	v_fmac_f32_e32 v68, v98, v14
	v_fmac_f32_e32 v70, v98, v20
	v_fmac_f32_e32 v71, v98, v21
	s_waitcnt lgkmcnt(2)
	v_fmac_f32_e32 v75, v98, v24
	v_fmac_f32_e32 v46, v97, v37
	v_fmac_f32_e32 v69, v97, v20
	v_fmac_f32_e32 v44, v96, v36
	v_fmac_f32_e32 v45, v96, v37
	v_fmac_f32_e32 v43, v95, v36
	v_fmac_f32_e32 v42, v94, v36
	v_fmac_f32_e32 v41, v93, v36
	v_fmac_f32_e32 v47, v97, v38
	v_fmac_f32_e32 v48, v97, v39
	v_fmac_f32_e32 v49, v97, v34
	v_fmac_f32_e32 v50, v97, v35
	v_fmac_f32_e32 v51, v97, v30
	v_fmac_f32_e32 v52, v97, v31
	v_fmac_f32_e32 v53, v97, v26
	v_fmac_f32_e32 v54, v97, v27
	v_fmac_f32_e32 v55, v97, v22
	v_fmac_f32_e32 v56, v97, v23
	v_fmac_f32_e32 v57, v97, v18
	v_fmac_f32_e32 v58, v97, v19
	v_fmac_f32_e32 v59, v97, v16
	v_fmac_f32_e32 v60, v97, v17
	v_fmac_f32_e32 v61, v97, v12
	v_fmac_f32_e32 v62, v97, v13
	v_fmac_f32_e32 v63, v97, v8
	v_fmac_f32_e32 v64, v97, v9
	v_fmac_f32_e32 v65, v97, v10
	v_fmac_f32_e32 v66, v97, v11
	v_fmac_f32_e32 v67, v97, v14
	v_fmac_f32_e32 v68, v97, v15
	v_fmac_f32_e32 v70, v97, v21
	v_fmac_f32_e32 v71, v97, v24
	v_fmac_f32_e32 v75, v97, v25
	v_fmac_f32_e32 v46, v96, v38
	v_fmac_f32_e32 v69, v96, v21
	v_fmac_f32_e32 v44, v95, v37
	v_fmac_f32_e32 v45, v95, v38
	v_fmac_f32_e32 v43, v94, v37
	v_fmac_f32_e32 v42, v93, v37
	v_fmac_f32_e32 v41, v92, v37
	ds_read2st64_b32 v[36:37], v40 offset0:176 offset1:180
	v_fmac_f32_e32 v47, v96, v39
	v_fmac_f32_e32 v48, v96, v34
	v_fmac_f32_e32 v49, v96, v35
	v_fmac_f32_e32 v50, v96, v30
	v_fmac_f32_e32 v51, v96, v31
	v_fmac_f32_e32 v52, v96, v26
	v_fmac_f32_e32 v53, v96, v27
	v_fmac_f32_e32 v54, v96, v22
	v_fmac_f32_e32 v55, v96, v23
	v_fmac_f32_e32 v56, v96, v18
	v_fmac_f32_e32 v57, v96, v19
	v_fmac_f32_e32 v58, v96, v16
	v_fmac_f32_e32 v59, v96, v17
	v_fmac_f32_e32 v60, v96, v12
	v_fmac_f32_e32 v61, v96, v13
	v_fmac_f32_e32 v62, v96, v8
	v_fmac_f32_e32 v63, v96, v9
	v_fmac_f32_e32 v64, v96, v10
	v_fmac_f32_e32 v65, v96, v11
	v_fmac_f32_e32 v66, v96, v14
	v_fmac_f32_e32 v67, v96, v15
	v_fmac_f32_e32 v68, v96, v20
	v_fmac_f32_e32 v70, v96, v24
	v_fmac_f32_e32 v71, v96, v25
	s_waitcnt lgkmcnt(2)
	v_fmac_f32_e32 v75, v96, v28
	v_fmac_f32_e32 v46, v95, v39
	v_fmac_f32_e32 v69, v95, v24
	v_fmac_f32_e32 v44, v94, v38
	v_fmac_f32_e32 v45, v94, v39
	v_fmac_f32_e32 v43, v93, v38
	v_fmac_f32_e32 v42, v92, v38
	v_fmac_f32_e32 v41, v91, v38
	v_fmac_f32_e32 v47, v95, v34
	v_fmac_f32_e32 v48, v95, v35
	v_fmac_f32_e32 v49, v95, v30
	v_fmac_f32_e32 v50, v95, v31
	v_fmac_f32_e32 v51, v95, v26
	v_fmac_f32_e32 v52, v95, v27
	v_fmac_f32_e32 v53, v95, v22
	v_fmac_f32_e32 v54, v95, v23
	v_fmac_f32_e32 v55, v95, v18
	v_fmac_f32_e32 v56, v95, v19
	v_fmac_f32_e32 v57, v95, v16
	v_fmac_f32_e32 v58, v95, v17
	v_fmac_f32_e32 v59, v95, v12
	v_fmac_f32_e32 v60, v95, v13
	v_fmac_f32_e32 v61, v95, v8
	v_fmac_f32_e32 v62, v95, v9
	v_fmac_f32_e32 v63, v95, v10
	v_fmac_f32_e32 v64, v95, v11
	v_fmac_f32_e32 v65, v95, v14
	v_fmac_f32_e32 v66, v95, v15
	v_fmac_f32_e32 v67, v95, v20
	v_fmac_f32_e32 v68, v95, v21
	v_fmac_f32_e32 v70, v95, v25
	v_fmac_f32_e32 v71, v95, v28
	v_fmac_f32_e32 v75, v95, v29
	v_fmac_f32_e32 v46, v94, v34
	v_fmac_f32_e32 v69, v94, v25
	v_fmac_f32_e32 v44, v93, v39
	v_fmac_f32_e32 v45, v93, v34
	v_fmac_f32_e32 v43, v92, v39
	v_fmac_f32_e32 v42, v91, v39
	v_fmac_f32_e32 v41, v90, v39
	ds_read2st64_b32 v[38:39], v40 offset0:184 offset1:188
	v_fmac_f32_e32 v47, v94, v35
	v_fmac_f32_e32 v48, v94, v30
	v_fmac_f32_e32 v49, v94, v31
	v_fmac_f32_e32 v50, v94, v26
	v_fmac_f32_e32 v51, v94, v27
	v_fmac_f32_e32 v52, v94, v22
	v_fmac_f32_e32 v53, v94, v23
	v_fmac_f32_e32 v54, v94, v18
	v_fmac_f32_e32 v55, v94, v19
	v_fmac_f32_e32 v56, v94, v16
	v_fmac_f32_e32 v57, v94, v17
	v_fmac_f32_e32 v58, v94, v12
	v_fmac_f32_e32 v59, v94, v13
	v_fmac_f32_e32 v60, v94, v8
	v_fmac_f32_e32 v61, v94, v9
	v_fmac_f32_e32 v62, v94, v10
	v_fmac_f32_e32 v63, v94, v11
	v_fmac_f32_e32 v64, v94, v14
	v_fmac_f32_e32 v65, v94, v15
	v_fmac_f32_e32 v66, v94, v20
	v_fmac_f32_e32 v67, v94, v21
	v_fmac_f32_e32 v68, v94, v24
	v_fmac_f32_e32 v70, v94, v28
	v_fmac_f32_e32 v71, v94, v29
	s_waitcnt lgkmcnt(2)
	v_fmac_f32_e32 v75, v94, v32
	v_fmac_f32_e32 v46, v93, v35
	v_fmac_f32_e32 v69, v93, v28
	v_fmac_f32_e32 v44, v92, v34
	v_fmac_f32_e32 v45, v92, v35
	v_fmac_f32_e32 v43, v91, v34
	v_fmac_f32_e32 v42, v90, v34
	v_fmac_f32_e32 v41, v89, v34
	v_fmac_f32_e32 v47, v93, v30
	v_fmac_f32_e32 v48, v93, v31
	v_fmac_f32_e32 v49, v93, v26
	v_fmac_f32_e32 v50, v93, v27
	v_fmac_f32_e32 v51, v93, v22
	v_fmac_f32_e32 v52, v93, v23
	v_fmac_f32_e32 v53, v93, v18
	v_fmac_f32_e32 v54, v93, v19
	v_fmac_f32_e32 v55, v93, v16
	v_fmac_f32_e32 v56, v93, v17
	v_fmac_f32_e32 v57, v93, v12
	v_fmac_f32_e32 v58, v93, v13
	v_fmac_f32_e32 v59, v93, v8
	v_fmac_f32_e32 v60, v93, v9
	v_fmac_f32_e32 v61, v93, v10
	v_fmac_f32_e32 v62, v93, v11
	v_fmac_f32_e32 v63, v93, v14
	v_fmac_f32_e32 v64, v93, v15
	v_fmac_f32_e32 v65, v93, v20
	v_fmac_f32_e32 v66, v93, v21
	v_fmac_f32_e32 v67, v93, v24
	v_fmac_f32_e32 v68, v93, v25
	v_fmac_f32_e32 v70, v93, v29
	v_fmac_f32_e32 v71, v93, v32
	v_fmac_f32_e32 v75, v93, v33
	v_fmac_f32_e32 v46, v92, v30
	v_fmac_f32_e32 v69, v92, v29
	v_fmac_f32_e32 v44, v91, v35
	v_fmac_f32_e32 v45, v91, v30
	v_fmac_f32_e32 v43, v90, v35
	v_fmac_f32_e32 v42, v89, v35
	v_fmac_f32_e32 v41, v88, v35
	ds_read2st64_b32 v[34:35], v40 offset0:192 offset1:196
	v_fmac_f32_e32 v47, v92, v31
	v_fmac_f32_e32 v48, v92, v26
	v_fmac_f32_e32 v49, v92, v27
	v_fmac_f32_e32 v50, v92, v22
	v_fmac_f32_e32 v51, v92, v23
	v_fmac_f32_e32 v52, v92, v18
	v_fmac_f32_e32 v53, v92, v19
	v_fmac_f32_e32 v54, v92, v16
	v_fmac_f32_e32 v55, v92, v17
	v_fmac_f32_e32 v56, v92, v12
	v_fmac_f32_e32 v57, v92, v13
	v_fmac_f32_e32 v58, v92, v8
	v_fmac_f32_e32 v59, v92, v9
	v_fmac_f32_e32 v60, v92, v10
	v_fmac_f32_e32 v61, v92, v11
	v_fmac_f32_e32 v62, v92, v14
	v_fmac_f32_e32 v63, v92, v15
	v_fmac_f32_e32 v64, v92, v20
	v_fmac_f32_e32 v65, v92, v21
	v_fmac_f32_e32 v66, v92, v24
	v_fmac_f32_e32 v67, v92, v25
	v_fmac_f32_e32 v68, v92, v28
	v_fmac_f32_e32 v70, v92, v32
	v_fmac_f32_e32 v71, v92, v33
	s_waitcnt lgkmcnt(2)
	v_fmac_f32_e32 v75, v92, v36
	v_fmac_f32_e32 v46, v91, v31
	v_fmac_f32_e32 v69, v91, v32
	v_fmac_f32_e32 v44, v90, v30
	v_fmac_f32_e32 v45, v90, v31
	v_fmac_f32_e32 v43, v89, v30
	v_fmac_f32_e32 v42, v88, v30
	v_fmac_f32_e32 v41, v87, v30
	v_fmac_f32_e32 v47, v91, v26
	v_fmac_f32_e32 v48, v91, v27
	v_fmac_f32_e32 v49, v91, v22
	v_fmac_f32_e32 v50, v91, v23
	v_fmac_f32_e32 v51, v91, v18
	v_fmac_f32_e32 v52, v91, v19
	v_fmac_f32_e32 v53, v91, v16
	v_fmac_f32_e32 v54, v91, v17
	v_fmac_f32_e32 v55, v91, v12
	v_fmac_f32_e32 v56, v91, v13
	v_fmac_f32_e32 v57, v91, v8
	v_fmac_f32_e32 v58, v91, v9
	v_fmac_f32_e32 v59, v91, v10
	v_fmac_f32_e32 v60, v91, v11
	v_fmac_f32_e32 v61, v91, v14
	v_fmac_f32_e32 v62, v91, v15
	v_fmac_f32_e32 v63, v91, v20
	v_fmac_f32_e32 v64, v91, v21
	v_fmac_f32_e32 v65, v91, v24
	v_fmac_f32_e32 v66, v91, v25
	v_fmac_f32_e32 v67, v91, v28
	v_fmac_f32_e32 v68, v91, v29
	v_fmac_f32_e32 v70, v91, v33
	v_fmac_f32_e32 v71, v91, v36
	v_fmac_f32_e32 v75, v91, v37
	v_fmac_f32_e32 v46, v90, v26
	v_fmac_f32_e32 v69, v90, v33
	v_fmac_f32_e32 v44, v89, v31
	v_fmac_f32_e32 v45, v89, v26
	v_fmac_f32_e32 v43, v88, v31
	v_fmac_f32_e32 v42, v87, v31
	v_fmac_f32_e32 v41, v86, v31
	ds_read2st64_b32 v[30:31], v40 offset0:200 offset1:204
	v_fmac_f32_e32 v47, v90, v27
	v_fmac_f32_e32 v48, v90, v22
	v_fmac_f32_e32 v49, v90, v23
	v_fmac_f32_e32 v50, v90, v18
	v_fmac_f32_e32 v51, v90, v19
	v_fmac_f32_e32 v52, v90, v16
	v_fmac_f32_e32 v53, v90, v17
	v_fmac_f32_e32 v54, v90, v12
	v_fmac_f32_e32 v55, v90, v13
	v_fmac_f32_e32 v56, v90, v8
	v_fmac_f32_e32 v57, v90, v9
	v_fmac_f32_e32 v58, v90, v10
	v_fmac_f32_e32 v59, v90, v11
	v_fmac_f32_e32 v60, v90, v14
	v_fmac_f32_e32 v61, v90, v15
	v_fmac_f32_e32 v62, v90, v20
	v_fmac_f32_e32 v63, v90, v21
	v_fmac_f32_e32 v64, v90, v24
	v_fmac_f32_e32 v65, v90, v25
	v_fmac_f32_e32 v66, v90, v28
	v_fmac_f32_e32 v67, v90, v29
	v_fmac_f32_e32 v68, v90, v32
	v_fmac_f32_e32 v70, v90, v36
	v_fmac_f32_e32 v71, v90, v37
	s_waitcnt lgkmcnt(2)
	v_fmac_f32_e32 v75, v90, v38
	v_fmac_f32_e32 v46, v89, v27
	v_fmac_f32_e32 v69, v89, v36
	v_fmac_f32_e32 v44, v88, v26
	v_fmac_f32_e32 v45, v88, v27
	v_fmac_f32_e32 v43, v87, v26
	v_fmac_f32_e32 v42, v86, v26
	v_fmac_f32_e32 v41, v85, v26
	v_fmac_f32_e32 v47, v89, v22
	v_fmac_f32_e32 v48, v89, v23
	v_fmac_f32_e32 v49, v89, v18
	v_fmac_f32_e32 v50, v89, v19
	v_fmac_f32_e32 v51, v89, v16
	v_fmac_f32_e32 v52, v89, v17
	v_fmac_f32_e32 v53, v89, v12
	v_fmac_f32_e32 v54, v89, v13
	v_fmac_f32_e32 v55, v89, v8
	v_fmac_f32_e32 v56, v89, v9
	v_fmac_f32_e32 v57, v89, v10
	v_fmac_f32_e32 v58, v89, v11
	v_fmac_f32_e32 v59, v89, v14
	v_fmac_f32_e32 v60, v89, v15
	v_fmac_f32_e32 v61, v89, v20
	v_fmac_f32_e32 v62, v89, v21
	v_fmac_f32_e32 v63, v89, v24
	v_fmac_f32_e32 v64, v89, v25
	v_fmac_f32_e32 v65, v89, v28
	v_fmac_f32_e32 v66, v89, v29
	v_fmac_f32_e32 v67, v89, v32
	v_fmac_f32_e32 v68, v89, v33
	v_fmac_f32_e32 v70, v89, v37
	v_fmac_f32_e32 v71, v89, v38
	v_fmac_f32_e32 v75, v89, v39
	v_fmac_f32_e32 v46, v88, v22
	v_fmac_f32_e32 v69, v88, v37
	v_fmac_f32_e32 v44, v87, v27
	v_fmac_f32_e32 v45, v87, v22
	v_fmac_f32_e32 v43, v86, v27
	v_fmac_f32_e32 v42, v85, v27
	v_fmac_f32_e32 v41, v84, v27
	ds_read2st64_b32 v[26:27], v40 offset0:208 offset1:212
	v_fmac_f32_e32 v47, v88, v23
	v_fmac_f32_e32 v48, v88, v18
	v_fmac_f32_e32 v49, v88, v19
	v_fmac_f32_e32 v50, v88, v16
	v_fmac_f32_e32 v51, v88, v17
	v_fmac_f32_e32 v52, v88, v12
	v_fmac_f32_e32 v53, v88, v13
	v_fmac_f32_e32 v54, v88, v8
	v_fmac_f32_e32 v55, v88, v9
	v_fmac_f32_e32 v56, v88, v10
	v_fmac_f32_e32 v57, v88, v11
	v_fmac_f32_e32 v58, v88, v14
	v_fmac_f32_e32 v59, v88, v15
	v_fmac_f32_e32 v60, v88, v20
	v_fmac_f32_e32 v61, v88, v21
	v_fmac_f32_e32 v62, v88, v24
	v_fmac_f32_e32 v63, v88, v25
	v_fmac_f32_e32 v64, v88, v28
	v_fmac_f32_e32 v65, v88, v29
	v_fmac_f32_e32 v66, v88, v32
	v_fmac_f32_e32 v67, v88, v33
	v_fmac_f32_e32 v68, v88, v36
	v_fmac_f32_e32 v70, v88, v38
	v_fmac_f32_e32 v71, v88, v39
	s_waitcnt lgkmcnt(2)
	v_fmac_f32_e32 v75, v88, v34
	v_fmac_f32_e32 v46, v87, v23
	v_fmac_f32_e32 v69, v87, v38
	v_fmac_f32_e32 v44, v86, v22
	v_fmac_f32_e32 v45, v86, v23
	v_fmac_f32_e32 v43, v85, v22
	v_fmac_f32_e32 v42, v84, v22
	v_fmac_f32_e32 v41, v83, v22
	v_fmac_f32_e32 v47, v87, v18
	v_fmac_f32_e32 v48, v87, v19
	v_fmac_f32_e32 v49, v87, v16
	v_fmac_f32_e32 v50, v87, v17
	v_fmac_f32_e32 v51, v87, v12
	v_fmac_f32_e32 v52, v87, v13
	v_fmac_f32_e32 v53, v87, v8
	v_fmac_f32_e32 v54, v87, v9
	v_fmac_f32_e32 v55, v87, v10
	v_fmac_f32_e32 v56, v87, v11
	v_fmac_f32_e32 v57, v87, v14
	v_fmac_f32_e32 v58, v87, v15
	v_fmac_f32_e32 v59, v87, v20
	v_fmac_f32_e32 v60, v87, v21
	v_fmac_f32_e32 v61, v87, v24
	v_fmac_f32_e32 v62, v87, v25
	v_fmac_f32_e32 v63, v87, v28
	v_fmac_f32_e32 v64, v87, v29
	v_fmac_f32_e32 v65, v87, v32
	v_fmac_f32_e32 v66, v87, v33
	v_fmac_f32_e32 v67, v87, v36
	v_fmac_f32_e32 v68, v87, v37
	v_fmac_f32_e32 v70, v87, v39
	v_fmac_f32_e32 v71, v87, v34
	v_fmac_f32_e32 v75, v87, v35
	v_fmac_f32_e32 v46, v86, v18
	v_fmac_f32_e32 v69, v86, v39
	v_fmac_f32_e32 v44, v85, v23
	v_fmac_f32_e32 v45, v85, v18
	v_fmac_f32_e32 v43, v84, v23
	v_fmac_f32_e32 v42, v83, v23
	v_fmac_f32_e32 v41, v82, v23
	ds_read2st64_b32 v[22:23], v40 offset0:216 offset1:220
	v_fmac_f32_e32 v47, v86, v19
	v_fmac_f32_e32 v48, v86, v16
	v_fmac_f32_e32 v49, v86, v17
	v_fmac_f32_e32 v50, v86, v12
	v_fmac_f32_e32 v51, v86, v13
	v_fmac_f32_e32 v52, v86, v8
	v_fmac_f32_e32 v53, v86, v9
	v_fmac_f32_e32 v54, v86, v10
	v_fmac_f32_e32 v55, v86, v11
	v_fmac_f32_e32 v56, v86, v14
	v_fmac_f32_e32 v57, v86, v15
	v_fmac_f32_e32 v58, v86, v20
	v_fmac_f32_e32 v59, v86, v21
	v_fmac_f32_e32 v60, v86, v24
	v_fmac_f32_e32 v61, v86, v25
	v_fmac_f32_e32 v62, v86, v28
	v_fmac_f32_e32 v63, v86, v29
	v_fmac_f32_e32 v64, v86, v32
	v_fmac_f32_e32 v65, v86, v33
	v_fmac_f32_e32 v66, v86, v36
	v_fmac_f32_e32 v67, v86, v37
	v_fmac_f32_e32 v68, v86, v38
	v_fmac_f32_e32 v70, v86, v34
	v_fmac_f32_e32 v71, v86, v35
	s_waitcnt lgkmcnt(2)
	v_fmac_f32_e32 v75, v86, v30
	v_fmac_f32_e32 v46, v85, v19
	v_fmac_f32_e32 v69, v85, v34
	v_fmac_f32_e32 v44, v84, v18
	v_fmac_f32_e32 v45, v84, v19
	v_fmac_f32_e32 v43, v83, v18
	v_fmac_f32_e32 v42, v82, v18
	v_fmac_f32_e32 v41, v81, v18
	v_fmac_f32_e32 v47, v85, v16
	v_fmac_f32_e32 v48, v85, v17
	v_fmac_f32_e32 v49, v85, v12
	v_fmac_f32_e32 v50, v85, v13
	v_fmac_f32_e32 v51, v85, v8
	v_fmac_f32_e32 v52, v85, v9
	v_fmac_f32_e32 v53, v85, v10
	v_fmac_f32_e32 v54, v85, v11
	v_fmac_f32_e32 v55, v85, v14
	v_fmac_f32_e32 v56, v85, v15
	v_fmac_f32_e32 v57, v85, v20
	v_fmac_f32_e32 v58, v85, v21
	v_fmac_f32_e32 v59, v85, v24
	v_fmac_f32_e32 v60, v85, v25
	v_fmac_f32_e32 v61, v85, v28
	v_fmac_f32_e32 v62, v85, v29
	v_fmac_f32_e32 v63, v85, v32
	v_fmac_f32_e32 v64, v85, v33
	v_fmac_f32_e32 v65, v85, v36
	v_fmac_f32_e32 v66, v85, v37
	v_fmac_f32_e32 v67, v85, v38
	v_fmac_f32_e32 v68, v85, v39
	v_fmac_f32_e32 v70, v85, v35
	v_fmac_f32_e32 v71, v85, v30
	v_fmac_f32_e32 v75, v85, v31
	v_fmac_f32_e32 v46, v84, v16
	v_fmac_f32_e32 v69, v84, v35
	v_fmac_f32_e32 v44, v83, v19
	v_fmac_f32_e32 v45, v83, v16
	v_fmac_f32_e32 v43, v82, v19
	v_fmac_f32_e32 v42, v81, v19
	v_fmac_f32_e32 v41, v80, v19
	ds_read2st64_b32 v[18:19], v40 offset0:224 offset1:228
	v_fmac_f32_e32 v47, v84, v17
	v_fmac_f32_e32 v48, v84, v12
	v_fmac_f32_e32 v49, v84, v13
	v_fmac_f32_e32 v50, v84, v8
	v_fmac_f32_e32 v51, v84, v9
	v_fmac_f32_e32 v52, v84, v10
	v_fmac_f32_e32 v53, v84, v11
	v_fmac_f32_e32 v54, v84, v14
	v_fmac_f32_e32 v55, v84, v15
	v_fmac_f32_e32 v56, v84, v20
	v_fmac_f32_e32 v57, v84, v21
	v_fmac_f32_e32 v58, v84, v24
	v_fmac_f32_e32 v59, v84, v25
	v_fmac_f32_e32 v60, v84, v28
	v_fmac_f32_e32 v61, v84, v29
	v_fmac_f32_e32 v62, v84, v32
	v_fmac_f32_e32 v63, v84, v33
	v_fmac_f32_e32 v64, v84, v36
	v_fmac_f32_e32 v65, v84, v37
	v_fmac_f32_e32 v66, v84, v38
	v_fmac_f32_e32 v67, v84, v39
	v_fmac_f32_e32 v68, v84, v34
	v_fmac_f32_e32 v70, v84, v30
	v_fmac_f32_e32 v71, v84, v31
	s_waitcnt lgkmcnt(2)
	v_fmac_f32_e32 v75, v84, v26
	v_fmac_f32_e32 v46, v83, v17
	v_fmac_f32_e32 v69, v83, v30
	v_fmac_f32_e32 v44, v82, v16
	v_fmac_f32_e32 v45, v82, v17
	v_fmac_f32_e32 v43, v81, v16
	v_fmac_f32_e32 v42, v80, v16
	v_fmac_f32_e32 v41, v79, v16
	v_fmac_f32_e32 v47, v83, v12
	v_fmac_f32_e32 v48, v83, v13
	v_fmac_f32_e32 v49, v83, v8
	v_fmac_f32_e32 v50, v83, v9
	v_fmac_f32_e32 v51, v83, v10
	v_fmac_f32_e32 v52, v83, v11
	v_fmac_f32_e32 v53, v83, v14
	v_fmac_f32_e32 v54, v83, v15
	v_fmac_f32_e32 v55, v83, v20
	v_fmac_f32_e32 v56, v83, v21
	v_fmac_f32_e32 v57, v83, v24
	v_fmac_f32_e32 v58, v83, v25
	v_fmac_f32_e32 v59, v83, v28
	v_fmac_f32_e32 v60, v83, v29
	v_fmac_f32_e32 v61, v83, v32
	v_fmac_f32_e32 v62, v83, v33
	v_fmac_f32_e32 v63, v83, v36
	v_fmac_f32_e32 v64, v83, v37
	v_fmac_f32_e32 v65, v83, v38
	v_fmac_f32_e32 v66, v83, v39
	v_fmac_f32_e32 v67, v83, v34
	v_fmac_f32_e32 v68, v83, v35
	v_fmac_f32_e32 v70, v83, v31
	v_fmac_f32_e32 v71, v83, v26
	v_fmac_f32_e32 v75, v83, v27
	v_fmac_f32_e32 v46, v82, v12
	v_fmac_f32_e32 v69, v82, v31
	v_fmac_f32_e32 v44, v81, v17
	v_fmac_f32_e32 v45, v81, v12
	v_fmac_f32_e32 v43, v80, v17
	v_fmac_f32_e32 v42, v79, v17
	v_fmac_f32_e32 v41, v78, v17
	ds_read2st64_b32 v[16:17], v40 offset0:232 offset1:236
	v_fmac_f32_e32 v47, v82, v13
	v_fmac_f32_e32 v48, v82, v8
	v_fmac_f32_e32 v49, v82, v9
	v_fmac_f32_e32 v50, v82, v10
	v_fmac_f32_e32 v51, v82, v11
	v_fmac_f32_e32 v52, v82, v14
	v_fmac_f32_e32 v53, v82, v15
	v_fmac_f32_e32 v54, v82, v20
	v_fmac_f32_e32 v55, v82, v21
	v_fmac_f32_e32 v56, v82, v24
	v_fmac_f32_e32 v57, v82, v25
	v_fmac_f32_e32 v58, v82, v28
	v_fmac_f32_e32 v59, v82, v29
	v_fmac_f32_e32 v60, v82, v32
	v_fmac_f32_e32 v61, v82, v33
	v_fmac_f32_e32 v62, v82, v36
	v_fmac_f32_e32 v63, v82, v37
	v_fmac_f32_e32 v64, v82, v38
	v_fmac_f32_e32 v65, v82, v39
	v_fmac_f32_e32 v66, v82, v34
	v_fmac_f32_e32 v67, v82, v35
	v_fmac_f32_e32 v68, v82, v30
	v_fmac_f32_e32 v70, v82, v26
	v_fmac_f32_e32 v71, v82, v27
	s_waitcnt lgkmcnt(2)
	v_fmac_f32_e32 v75, v82, v22
	v_fmac_f32_e32 v46, v81, v13
	v_fmac_f32_e32 v69, v81, v26
	v_fmac_f32_e32 v44, v80, v12
	v_fmac_f32_e32 v45, v80, v13
	v_fmac_f32_e32 v43, v79, v12
	v_fmac_f32_e32 v42, v78, v12
	v_fmac_f32_e32 v41, v77, v12
	v_fmac_f32_e32 v47, v81, v8
	v_fmac_f32_e32 v48, v81, v9
	v_fmac_f32_e32 v49, v81, v10
	v_fmac_f32_e32 v50, v81, v11
	v_fmac_f32_e32 v51, v81, v14
	v_fmac_f32_e32 v52, v81, v15
	v_fmac_f32_e32 v53, v81, v20
	v_fmac_f32_e32 v54, v81, v21
	v_fmac_f32_e32 v55, v81, v24
	v_fmac_f32_e32 v56, v81, v25
	v_fmac_f32_e32 v57, v81, v28
	v_fmac_f32_e32 v58, v81, v29
	v_fmac_f32_e32 v59, v81, v32
	v_fmac_f32_e32 v60, v81, v33
	v_fmac_f32_e32 v61, v81, v36
	v_fmac_f32_e32 v62, v81, v37
	v_fmac_f32_e32 v63, v81, v38
	v_fmac_f32_e32 v64, v81, v39
	v_fmac_f32_e32 v65, v81, v34
	v_fmac_f32_e32 v66, v81, v35
	v_fmac_f32_e32 v67, v81, v30
	v_fmac_f32_e32 v68, v81, v31
	v_fmac_f32_e32 v70, v81, v27
	v_fmac_f32_e32 v71, v81, v22
	v_fmac_f32_e32 v75, v81, v23
	v_fmac_f32_e32 v46, v80, v8
	v_fmac_f32_e32 v69, v80, v27
	v_fmac_f32_e32 v44, v79, v13
	v_fmac_f32_e32 v45, v79, v8
	v_fmac_f32_e32 v43, v78, v13
	v_fmac_f32_e32 v42, v77, v13
	v_fmac_f32_e32 v41, v76, v13
	ds_read2st64_b32 v[12:13], v40 offset0:240 offset1:244
	v_fmac_f32_e32 v47, v80, v9
	v_fmac_f32_e32 v48, v80, v10
	v_fmac_f32_e32 v49, v80, v11
	v_fmac_f32_e32 v50, v80, v14
	v_fmac_f32_e32 v51, v80, v15
	v_fmac_f32_e32 v52, v80, v20
	v_fmac_f32_e32 v53, v80, v21
	v_fmac_f32_e32 v54, v80, v24
	v_fmac_f32_e32 v55, v80, v25
	v_fmac_f32_e32 v56, v80, v28
	v_fmac_f32_e32 v57, v80, v29
	v_fmac_f32_e32 v58, v80, v32
	v_fmac_f32_e32 v59, v80, v33
	v_fmac_f32_e32 v60, v80, v36
	v_fmac_f32_e32 v61, v80, v37
	v_fmac_f32_e32 v62, v80, v38
	v_fmac_f32_e32 v63, v80, v39
	v_fmac_f32_e32 v64, v80, v34
	v_fmac_f32_e32 v65, v80, v35
	v_fmac_f32_e32 v66, v80, v30
	v_fmac_f32_e32 v67, v80, v31
	v_fmac_f32_e32 v68, v80, v26
	v_fmac_f32_e32 v70, v80, v22
	v_fmac_f32_e32 v71, v80, v23
	s_waitcnt lgkmcnt(2)
	v_fmac_f32_e32 v75, v80, v18
	v_fmac_f32_e32 v46, v79, v9
	v_fmac_f32_e32 v69, v79, v22
	v_fmac_f32_e32 v45, v78, v9
	v_fmac_f32_e32 v47, v79, v10
	v_fmac_f32_e32 v48, v79, v11
	v_fmac_f32_e32 v49, v79, v14
	v_fmac_f32_e32 v50, v79, v15
	v_fmac_f32_e32 v51, v79, v20
	v_fmac_f32_e32 v52, v79, v21
	v_fmac_f32_e32 v53, v79, v24
	v_fmac_f32_e32 v54, v79, v25
	v_fmac_f32_e32 v55, v79, v28
	v_fmac_f32_e32 v56, v79, v29
	v_fmac_f32_e32 v57, v79, v32
	v_fmac_f32_e32 v58, v79, v33
	v_fmac_f32_e32 v59, v79, v36
	v_fmac_f32_e32 v60, v79, v37
	v_fmac_f32_e32 v61, v79, v38
	v_fmac_f32_e32 v62, v79, v39
	v_fmac_f32_e32 v63, v79, v34
	v_fmac_f32_e32 v64, v79, v35
	v_fmac_f32_e32 v65, v79, v30
	v_fmac_f32_e32 v66, v79, v31
	v_fmac_f32_e32 v67, v79, v26
	v_fmac_f32_e32 v68, v79, v27
	v_fmac_f32_e32 v70, v79, v23
	v_fmac_f32_e32 v71, v79, v18
	v_fmac_f32_e32 v75, v79, v19
	v_fmac_f32_e32 v46, v78, v10
	v_fmac_f32_e32 v69, v78, v23
	v_fmac_f32_e32 v45, v77, v10
	v_fmac_f32_e32 v44, v78, v8
	v_fmac_f32_e32 v47, v78, v11
	v_fmac_f32_e32 v48, v78, v14
	v_fmac_f32_e32 v49, v78, v15
	v_fmac_f32_e32 v50, v78, v20
	v_fmac_f32_e32 v51, v78, v21
	v_fmac_f32_e32 v52, v78, v24
	v_fmac_f32_e32 v53, v78, v25
	v_fmac_f32_e32 v54, v78, v28
	v_fmac_f32_e32 v55, v78, v29
	v_fmac_f32_e32 v56, v78, v32
	v_fmac_f32_e32 v57, v78, v33
	v_fmac_f32_e32 v58, v78, v36
	v_fmac_f32_e32 v59, v78, v37
	v_fmac_f32_e32 v60, v78, v38
	v_fmac_f32_e32 v61, v78, v39
	v_fmac_f32_e32 v62, v78, v34
	v_fmac_f32_e32 v63, v78, v35
	v_fmac_f32_e32 v64, v78, v30
	v_fmac_f32_e32 v65, v78, v31
	v_fmac_f32_e32 v66, v78, v26
	v_fmac_f32_e32 v67, v78, v27
	v_fmac_f32_e32 v68, v78, v22
	v_fmac_f32_e32 v70, v78, v18
	v_fmac_f32_e32 v71, v78, v19
	s_waitcnt lgkmcnt(1)
	v_fmac_f32_e32 v75, v78, v16
	v_fmac_f32_e32 v43, v77, v8
	v_fmac_f32_e32 v46, v77, v11
	v_fmac_f32_e32 v69, v77, v18
	v_fmac_f32_e32 v42, v76, v8
	v_fmac_f32_e32 v45, v76, v11
	v_fmac_f32_e32 v41, v74, v8
	v_and_b32_e32 v8, 0xffffffcf, v122
	v_fmac_f32_e32 v44, v77, v9
	v_fmac_f32_e32 v47, v77, v14
	v_fmac_f32_e32 v48, v77, v15
	v_fmac_f32_e32 v49, v77, v20
	v_fmac_f32_e32 v50, v77, v21
	v_fmac_f32_e32 v51, v77, v24
	v_fmac_f32_e32 v52, v77, v25
	v_fmac_f32_e32 v53, v77, v28
	v_fmac_f32_e32 v54, v77, v29
	v_fmac_f32_e32 v55, v77, v32
	v_fmac_f32_e32 v56, v77, v33
	v_fmac_f32_e32 v57, v77, v36
	v_fmac_f32_e32 v58, v77, v37
	v_fmac_f32_e32 v59, v77, v38
	v_fmac_f32_e32 v60, v77, v39
	v_fmac_f32_e32 v61, v77, v34
	v_fmac_f32_e32 v62, v77, v35
	v_fmac_f32_e32 v63, v77, v30
	v_fmac_f32_e32 v64, v77, v31
	v_fmac_f32_e32 v65, v77, v26
	v_fmac_f32_e32 v66, v77, v27
	v_fmac_f32_e32 v67, v77, v22
	v_fmac_f32_e32 v68, v77, v23
	v_fmac_f32_e32 v70, v77, v19
	v_fmac_f32_e32 v71, v77, v16
	v_fmac_f32_e32 v75, v77, v17
	v_fmac_f32_e32 v43, v76, v9
	v_fmac_f32_e32 v46, v76, v14
	v_fmac_f32_e32 v69, v76, v19
	v_fmac_f32_e32 v42, v74, v9
	v_fmac_f32_e32 v45, v74, v14
	v_ashrrev_i32_e32 v9, 31, v8
	v_or_b32_e32 v14, 16, v8
	v_fmac_f32_e32 v44, v76, v10
	v_fmac_f32_e32 v47, v76, v15
	v_fmac_f32_e32 v48, v76, v20
	v_fmac_f32_e32 v49, v76, v21
	v_fmac_f32_e32 v50, v76, v24
	v_fmac_f32_e32 v51, v76, v25
	v_fmac_f32_e32 v52, v76, v28
	v_fmac_f32_e32 v53, v76, v29
	v_fmac_f32_e32 v54, v76, v32
	v_fmac_f32_e32 v55, v76, v33
	v_fmac_f32_e32 v56, v76, v36
	v_fmac_f32_e32 v57, v76, v37
	v_fmac_f32_e32 v58, v76, v38
	v_fmac_f32_e32 v59, v76, v39
	v_fmac_f32_e32 v60, v76, v34
	v_fmac_f32_e32 v61, v76, v35
	v_fmac_f32_e32 v62, v76, v30
	v_fmac_f32_e32 v63, v76, v31
	v_fmac_f32_e32 v64, v76, v26
	v_fmac_f32_e32 v65, v76, v27
	v_fmac_f32_e32 v66, v76, v22
	v_fmac_f32_e32 v67, v76, v23
	v_fmac_f32_e32 v68, v76, v18
	v_fmac_f32_e32 v70, v76, v16
	v_fmac_f32_e32 v71, v76, v17
	s_waitcnt lgkmcnt(0)
	v_fmac_f32_e32 v75, v76, v12
	v_fmac_f32_e32 v46, v74, v15
	v_fmac_f32_e32 v69, v74, v16
	v_and_b32_e32 v200, 48, v123
	v_lshlrev_b64 v[106:107], 9, v[8:9]
	v_ashrrev_i32_e32 v15, 31, v14
	v_or_b32_e32 v8, 32, v8
	v_or_b32_e32 v16, 48, v122
	v_fmac_f32_e32 v43, v74, v10
	v_fmac_f32_e32 v44, v74, v11
	v_fmac_f32_e32 v47, v74, v20
	v_fmac_f32_e32 v48, v74, v21
	v_fmac_f32_e32 v49, v74, v24
	v_fmac_f32_e32 v50, v74, v25
	v_fmac_f32_e32 v51, v74, v28
	v_fmac_f32_e32 v52, v74, v29
	v_fmac_f32_e32 v53, v74, v32
	v_fmac_f32_e32 v54, v74, v33
	v_fmac_f32_e32 v55, v74, v36
	v_fmac_f32_e32 v56, v74, v37
	v_fmac_f32_e32 v57, v74, v38
	v_fmac_f32_e32 v58, v74, v39
	v_fmac_f32_e32 v59, v74, v34
	v_fmac_f32_e32 v60, v74, v35
	v_fmac_f32_e32 v61, v74, v30
	v_fmac_f32_e32 v62, v74, v31
	v_fmac_f32_e32 v63, v74, v26
	v_fmac_f32_e32 v64, v74, v27
	v_fmac_f32_e32 v65, v74, v22
	v_fmac_f32_e32 v66, v74, v23
	v_fmac_f32_e32 v67, v74, v18
	v_fmac_f32_e32 v68, v74, v19
	v_fmac_f32_e32 v70, v74, v17
	v_fmac_f32_e32 v71, v74, v12
	v_fmac_f32_e32 v75, v74, v13
	s_waitcnt lgkmcnt(0)
	s_barrier
	ds_write2st64_b32 v40, v41, v42 offset1:4
	ds_write2st64_b32 v40, v43, v44 offset0:8 offset1:12
	ds_write2st64_b32 v40, v45, v46 offset0:16 offset1:20
	ds_write2st64_b32 v40, v47, v48 offset0:24 offset1:28
	ds_write2st64_b32 v40, v49, v50 offset0:32 offset1:36
	ds_write2st64_b32 v40, v51, v52 offset0:40 offset1:44
	ds_write2st64_b32 v40, v53, v54 offset0:48 offset1:52
	ds_write2st64_b32 v40, v55, v56 offset0:56 offset1:60
	ds_write2st64_b32 v40, v57, v58 offset0:64 offset1:68
	ds_write2st64_b32 v40, v59, v60 offset0:72 offset1:76
	ds_write2st64_b32 v40, v61, v62 offset0:80 offset1:84
	ds_write2st64_b32 v40, v63, v64 offset0:88 offset1:92
	ds_write2st64_b32 v40, v65, v66 offset0:96 offset1:100
	ds_write2st64_b32 v40, v67, v68 offset0:104 offset1:108
	ds_write2st64_b32 v40, v69, v70 offset0:112 offset1:116
	ds_write2st64_b32 v40, v71, v75 offset0:120 offset1:124
	v_lshl_add_u64 v[10:11], s[86:87], 0, v[200:201]
	v_lshlrev_b64 v[110:111], 9, v[14:15]
	v_ashrrev_i32_e32 v9, 31, v8
	v_ashrrev_i32_e32 v17, 31, v16
	s_waitcnt lgkmcnt(0)
	s_barrier
	v_lshl_add_u64 v[12:13], v[10:11], 0, v[106:107]
	v_lshl_add_u64 v[14:15], v[10:11], 0, v[110:111]
	v_lshlrev_b64 v[112:113], 9, v[8:9]
	v_lshlrev_b64 v[108:109], 9, v[16:17]
	v_lshl_add_u32 v114, v124, 13, v102
	v_lshl_add_u64 v[8:9], v[10:11], 0, v[112:113]
	v_lshl_add_u64 v[10:11], v[10:11], 0, v[108:109]
	global_load_dwordx4 v[56:59], v[12:13], off
	global_load_dwordx4 v[40:43], v[12:13], off offset:64
	global_load_dwordx4 v[60:63], v[14:15], off
	global_load_dwordx4 v[44:47], v[14:15], off offset:64
	global_load_dwordx4 v[64:67], v[8:9], off
	global_load_dwordx4 v[48:51], v[8:9], off offset:64
	global_load_dwordx4 v[68:71], v[10:11], off
	global_load_dwordx4 v[52:55], v[10:11], off offset:64
	global_load_dwordx4 v[24:27], v[12:13], off offset:128
	global_load_dwordx4 v[20:23], v[12:13], off offset:192
	global_load_dwordx4 v[28:31], v[14:15], off offset:128
	s_nop 0
	global_load_dwordx4 v[12:15], v[14:15], off offset:192
	ds_read_b128 v[100:103], v114
	global_load_dwordx4 v[32:35], v[8:9], off offset:128
	global_load_dwordx4 v[16:19], v[8:9], off offset:192
	global_load_dwordx4 v[36:39], v[10:11], off offset:128
	s_nop 0
	global_load_dwordx4 v[8:11], v[10:11], off offset:192
	ds_read_b128 v[96:99], v114 offset:1024
	ds_read_b128 v[92:95], v114 offset:2048
	ds_read_b128 v[88:91], v114 offset:3072
	ds_read_b128 v[84:87], v114 offset:4096
	s_waitcnt lgkmcnt(4)
	v_mov_b32_e32 v72, v101
	v_mov_b32_e32 v73, v102
	v_mov_b32_e32 v74, v100
	v_mov_b32_e32 v75, v103
	v_pk_add_f32 v[72:73], v[72:73], v[74:75]
	s_waitcnt lgkmcnt(3)
	v_mov_b32_e32 v74, v96
	v_add_f32_e32 v118, v72, v73
	v_mov_b32_e32 v72, v97
	v_mov_b32_e32 v73, v98
	v_mov_b32_e32 v75, v99
	v_pk_add_f32 v[72:73], v[72:73], v[74:75]
	s_waitcnt lgkmcnt(2)
	v_mov_b32_e32 v74, v92
	v_add_f32_e32 v119, v72, v73
	v_mov_b32_e32 v72, v93
	v_mov_b32_e32 v73, v94
	v_mov_b32_e32 v75, v95
	v_pk_add_f32 v[72:73], v[72:73], v[74:75]
	ds_read_b128 v[80:83], v114 offset:5120
	ds_read_b128 v[76:79], v114 offset:6144
	v_add_f32_e32 v120, v72, v73
	s_waitcnt lgkmcnt(3)
	v_mov_b32_e32 v72, v89
	v_mov_b32_e32 v73, v90
	v_mov_b32_e32 v74, v88
	v_mov_b32_e32 v75, v91
	v_pk_add_f32 v[72:73], v[72:73], v[74:75]
	s_waitcnt lgkmcnt(2)
	v_mov_b32_e32 v74, v84
	v_add_f32_e32 v121, v72, v73
	v_mov_b32_e32 v72, v85
	v_mov_b32_e32 v73, v86
	v_mov_b32_e32 v75, v87
	v_pk_add_f32 v[72:73], v[72:73], v[74:75]
	s_waitcnt lgkmcnt(1)
	v_mov_b32_e32 v74, v80
	v_add_f32_e32 v126, v72, v73
	v_mov_b32_e32 v72, v81
	v_mov_b32_e32 v73, v82
	v_mov_b32_e32 v75, v83
	v_pk_add_f32 v[72:73], v[72:73], v[74:75]
	s_waitcnt lgkmcnt(0)
	v_mov_b32_e32 v115, v78
	v_add_f32_e32 v127, v72, v73
	ds_read_b128 v[72:75], v114 offset:7168
	v_mov_b32_e32 v114, v77
	v_mov_b32_e32 v116, v76
	v_mov_b32_e32 v117, v79
	v_pk_add_f32 v[114:115], v[114:115], v[116:117]
	s_waitcnt lgkmcnt(0)
	v_mov_b32_e32 v116, v72
	v_add_f32_e32 v128, v114, v115
	v_mov_b32_e32 v114, v73
	v_mov_b32_e32 v115, v74
	v_mov_b32_e32 v117, v75
	v_pk_add_f32 v[114:115], v[114:115], v[116:117]
	v_cmp_lt_i32_e32 vcc, v239, v238
	v_add_f32_e32 v114, v114, v115
	s_mov_b32 s0, 0x358637bd
	v_cndmask_b32_e32 v115, v237, v239, vcc
	v_lshlrev_b32_e32 v125, 2, v115
	ds_bpermute_b32 v116, v125, v119
	ds_bpermute_b32 v130, v125, v126
	ds_bpermute_b32 v115, v125, v118
	ds_bpermute_b32 v117, v125, v120
	ds_bpermute_b32 v131, v125, v127
	ds_bpermute_b32 v129, v125, v121
	ds_bpermute_b32 v132, v125, v128
	v_cmp_lt_i32_e32 vcc, v240, v238
	s_waitcnt lgkmcnt(6)
	v_add_f32_e32 v116, v119, v116
	s_waitcnt lgkmcnt(5)
	v_add_f32_e32 v119, v126, v130
	v_cndmask_b32_e32 v126, v237, v240, vcc
	s_waitcnt lgkmcnt(4)
	v_add_f32_e32 v115, v118, v115
	v_lshlrev_b32_e32 v126, 2, v126
	ds_bpermute_b32 v133, v125, v114
	s_waitcnt lgkmcnt(4)
	v_add_f32_e32 v117, v120, v117
	s_waitcnt lgkmcnt(3)
	v_add_f32_e32 v120, v127, v131
	ds_bpermute_b32 v127, v126, v115
	s_waitcnt lgkmcnt(3)
	v_add_f32_e32 v118, v121, v129
	s_waitcnt lgkmcnt(2)
	v_add_f32_e32 v121, v128, v132
	ds_bpermute_b32 v128, v126, v116
	ds_bpermute_b32 v129, v126, v117
	v_cmp_lt_i32_e32 vcc, v241, v238
	s_waitcnt lgkmcnt(3)
	v_add_f32_e32 v114, v114, v133
	s_waitcnt lgkmcnt(2)
	v_add_f32_e32 v115, v115, v127
	v_cndmask_b32_e32 v127, v237, v241, vcc
	ds_bpermute_b32 v130, v126, v118
	ds_bpermute_b32 v134, v126, v114
	v_lshlrev_b32_e32 v127, 2, v127
	ds_bpermute_b32 v131, v126, v119
	ds_bpermute_b32 v132, v126, v120
	ds_bpermute_b32 v133, v126, v121
	s_waitcnt lgkmcnt(6)
	v_add_f32_e32 v116, v116, v128
	ds_bpermute_b32 v128, v127, v115
	s_waitcnt lgkmcnt(6)
	v_add_f32_e32 v117, v117, v129
	ds_bpermute_b32 v129, v127, v116
	s_waitcnt lgkmcnt(6)
	v_add_f32_e32 v118, v118, v130
	s_waitcnt lgkmcnt(5)
	v_add_f32_e32 v114, v114, v134
	ds_bpermute_b32 v130, v127, v117
	v_cmp_lt_i32_e32 vcc, v242, v238
	s_waitcnt lgkmcnt(5)
	v_add_f32_e32 v119, v119, v131
	s_waitcnt lgkmcnt(4)
	v_add_f32_e32 v120, v120, v132
	s_waitcnt lgkmcnt(3)
	v_add_f32_e32 v121, v121, v133
	ds_bpermute_b32 v131, v127, v118
	ds_bpermute_b32 v135, v127, v114
	s_waitcnt lgkmcnt(4)
	v_add_f32_e32 v115, v115, v128
	v_cndmask_b32_e32 v128, v237, v242, vcc
	ds_bpermute_b32 v132, v127, v119
	ds_bpermute_b32 v133, v127, v120
	ds_bpermute_b32 v134, v127, v121
	v_lshlrev_b32_e32 v128, 2, v128
	s_waitcnt lgkmcnt(6)
	v_add_f32_e32 v116, v116, v129
	ds_bpermute_b32 v129, v128, v115
	s_waitcnt lgkmcnt(6)
	v_add_f32_e32 v117, v117, v130
	ds_bpermute_b32 v130, v128, v116
	s_waitcnt lgkmcnt(6)
	v_add_f32_e32 v118, v118, v131
	s_waitcnt lgkmcnt(5)
	v_add_f32_e32 v114, v114, v135
	ds_bpermute_b32 v131, v128, v117
	s_waitcnt lgkmcnt(5)
	v_add_f32_e32 v119, v119, v132
	s_waitcnt lgkmcnt(4)
	v_add_f32_e32 v120, v120, v133
	s_waitcnt lgkmcnt(3)
	v_add_f32_e32 v121, v121, v134
	ds_bpermute_b32 v132, v128, v118
	ds_bpermute_b32 v136, v128, v114
	v_cmp_lt_i32_e32 vcc, v243, v238
	ds_bpermute_b32 v133, v128, v119
	ds_bpermute_b32 v134, v128, v120
	ds_bpermute_b32 v135, v128, v121
	s_waitcnt lgkmcnt(7)
	v_add_f32_e32 v115, v115, v129
	v_cndmask_b32_e32 v129, v237, v243, vcc
	v_lshlrev_b32_e32 v129, 2, v129
	s_waitcnt lgkmcnt(6)
	v_add_f32_e32 v116, v116, v130
	ds_bpermute_b32 v130, v129, v115
	s_waitcnt lgkmcnt(6)
	v_add_f32_e32 v117, v117, v131
	s_waitcnt lgkmcnt(5)
	v_add_f32_e32 v118, v118, v132
	s_waitcnt lgkmcnt(4)
	v_add_f32_e32 v114, v114, v136
	ds_bpermute_b32 v131, v129, v116
	ds_bpermute_b32 v132, v129, v117
	s_waitcnt lgkmcnt(5)
	v_add_f32_e32 v119, v119, v133
	s_waitcnt lgkmcnt(4)
	v_add_f32_e32 v120, v120, v134
	s_waitcnt lgkmcnt(3)
	v_add_f32_e32 v121, v121, v135
	ds_bpermute_b32 v133, v129, v118
	ds_bpermute_b32 v137, v129, v114
	ds_bpermute_b32 v135, v129, v120
	ds_bpermute_b32 v136, v129, v121
	v_cmp_lt_i32_e32 vcc, v244, v238
	s_waitcnt lgkmcnt(6)
	v_add_f32_e32 v115, v115, v130
	ds_bpermute_b32 v134, v129, v119
	v_cndmask_b32_e32 v130, v237, v244, vcc
	v_lshlrev_b32_e32 v130, 2, v130
	s_waitcnt lgkmcnt(6)
	v_add_f32_e32 v116, v116, v131
	s_waitcnt lgkmcnt(5)
	v_add_f32_e32 v117, v117, v132
	ds_bpermute_b32 v131, v130, v115
	s_waitcnt lgkmcnt(5)
	v_add_f32_e32 v118, v118, v133
	s_waitcnt lgkmcnt(4)
	v_add_f32_e32 v114, v114, v137
	ds_bpermute_b32 v132, v130, v116
	ds_bpermute_b32 v133, v130, v117
	s_waitcnt lgkmcnt(5)
	v_add_f32_e32 v120, v120, v135
	s_waitcnt lgkmcnt(4)
	v_add_f32_e32 v121, v121, v136
	ds_bpermute_b32 v138, v130, v114
	ds_bpermute_b32 v136, v130, v120
	ds_bpermute_b32 v137, v130, v121
	s_waitcnt lgkmcnt(6)
	v_add_f32_e32 v119, v119, v134
	s_waitcnt lgkmcnt(5)
	v_add_f32_e32 v115, v115, v131
	ds_bpermute_b32 v134, v130, v118
	ds_bpermute_b32 v135, v130, v119
	s_waitcnt lgkmcnt(6)
	v_add_f32_e32 v131, v116, v132
	s_waitcnt lgkmcnt(5)
	v_add_f32_e32 v139, v117, v133
	v_fmamk_f32 v133, v115, 0xbb800000, v101
	v_fmamk_f32 v132, v115, 0xbb800000, v100
	v_fmamk_f32 v103, v115, 0xbb800000, v103
	v_fmac_f32_e32 v102, 0xbb800000, v115
	s_waitcnt lgkmcnt(4)
	v_add_f32_e32 v144, v114, v138
	v_pk_mul_f32 v[100:101], v[102:103], v[102:103]
	v_pk_mul_f32 v[114:115], v[132:133], v[132:133]
	s_waitcnt lgkmcnt(3)
	v_add_f32_e32 v142, v120, v136
	s_waitcnt lgkmcnt(2)
	v_add_f32_e32 v143, v121, v137
	v_pk_mov_b32 v[116:117], v[114:115], v[100:101] op_sel:[1,0]
	v_mov_b32_e32 v115, v101
	v_fmamk_f32 v121, v131, 0xbb800000, v97
	v_fmamk_f32 v120, v131, 0xbb800000, v96
	v_fmamk_f32 v99, v131, 0xbb800000, v99
	v_fmac_f32_e32 v98, 0xbb800000, v131
	v_pk_add_f32 v[100:101], v[116:117], v[114:115]
	v_pk_mul_f32 v[96:97], v[98:99], v[98:99]
	v_pk_mul_f32 v[114:115], v[120:121], v[120:121]
	s_waitcnt lgkmcnt(1)
	v_add_f32_e32 v140, v118, v134
	v_pk_mov_b32 v[116:117], v[114:115], v[96:97] op_sel:[1,0]
	v_mov_b32_e32 v115, v97
	s_waitcnt lgkmcnt(0)
	v_add_f32_e32 v141, v119, v135
	v_pk_add_f32 v[118:119], v[116:117], v[114:115]
	v_fmamk_f32 v117, v139, 0xbb800000, v93
	v_fmamk_f32 v116, v139, 0xbb800000, v92
	v_fmamk_f32 v95, v139, 0xbb800000, v95
	v_fmac_f32_e32 v94, 0xbb800000, v139
	v_pk_mul_f32 v[92:93], v[94:95], v[94:95]
	v_pk_mul_f32 v[96:97], v[116:117], v[116:117]
	v_fmamk_f32 v91, v140, 0xbb800000, v91
	v_pk_mov_b32 v[114:115], v[96:97], v[92:93] op_sel:[1,0]
	v_mov_b32_e32 v97, v93
	v_pk_add_f32 v[134:135], v[114:115], v[96:97]
	v_fmamk_f32 v97, v140, 0xbb800000, v89
	v_fmamk_f32 v96, v140, 0xbb800000, v88
	v_fmac_f32_e32 v90, 0xbb800000, v140
	v_pk_mul_f32 v[88:89], v[90:91], v[90:91]
	v_pk_mul_f32 v[92:93], v[96:97], v[96:97]
	v_fmamk_f32 v87, v141, 0xbb800000, v87
	v_pk_mov_b32 v[114:115], v[92:93], v[88:89] op_sel:[1,0]
	v_mov_b32_e32 v93, v89
	v_fmamk_f32 v89, v141, 0xbb800000, v85
	v_fmamk_f32 v88, v141, 0xbb800000, v84
	v_fmac_f32_e32 v86, 0xbb800000, v141
	v_pk_add_f32 v[136:137], v[114:115], v[92:93]
	v_pk_mul_f32 v[84:85], v[86:87], v[86:87]
	v_pk_mul_f32 v[92:93], v[88:89], v[88:89]
	v_fmamk_f32 v81, v142, 0xbb800000, v81
	v_pk_mov_b32 v[114:115], v[92:93], v[84:85] op_sel:[1,0]
	v_mov_b32_e32 v93, v85
	v_mov_b32_e32 v84, v118
	v_mov_b32_e32 v85, v100
	v_mov_b32_e32 v100, v119
	v_pk_add_f32 v[84:85], v[84:85], v[100:101]
	v_pk_add_f32 v[114:115], v[114:115], v[92:93]
	ds_bpermute_b32 v93, v125, v85
	ds_bpermute_b32 v92, v125, v84
	v_fmamk_f32 v80, v142, 0xbb800000, v80
	v_fmamk_f32 v83, v142, 0xbb800000, v83
	v_fmac_f32_e32 v82, 0xbb800000, v142
	v_pk_mul_f32 v[100:101], v[82:83], v[82:83]
	s_waitcnt lgkmcnt(0)
	v_pk_add_f32 v[84:85], v[84:85], v[92:93]
	ds_bpermute_b32 v93, v126, v85
	ds_bpermute_b32 v92, v126, v84
	v_pk_mul_f32 v[118:119], v[80:81], v[80:81]
	v_fmamk_f32 v77, v143, 0xbb800000, v77
	v_pk_mov_b32 v[138:139], v[118:119], v[100:101] op_sel:[1,0]
	v_mov_b32_e32 v119, v101
	s_waitcnt lgkmcnt(0)
	v_pk_add_f32 v[84:85], v[84:85], v[92:93]
	ds_bpermute_b32 v93, v127, v85
	ds_bpermute_b32 v92, v127, v84
	v_fmamk_f32 v76, v143, 0xbb800000, v76
	v_fmamk_f32 v79, v143, 0xbb800000, v79
	v_fmac_f32_e32 v78, 0xbb800000, v143
	v_pk_add_f32 v[118:119], v[138:139], v[118:119]
	s_waitcnt lgkmcnt(0)
	v_pk_add_f32 v[84:85], v[84:85], v[92:93]
	ds_bpermute_b32 v93, v128, v85
	ds_bpermute_b32 v92, v128, v84
	v_pk_mul_f32 v[100:101], v[78:79], v[78:79]
	v_pk_mul_f32 v[138:139], v[76:77], v[76:77]
	s_mov_b32 s28, 0x3b800000
	v_pk_mov_b32 v[140:141], v[138:139], v[100:101] op_sel:[1,0]
	s_waitcnt lgkmcnt(0)
	v_pk_add_f32 v[84:85], v[84:85], v[92:93]
	v_mov_b32_e32 v139, v101
	ds_bpermute_b32 v101, v129, v85
	ds_bpermute_b32 v100, v129, v84
	v_fmamk_f32 v73, v144, 0xbb800000, v73
	v_fmamk_f32 v72, v144, 0xbb800000, v72
	v_fmamk_f32 v75, v144, 0xbb800000, v75
	v_fmac_f32_e32 v74, 0xbb800000, v144
	s_waitcnt lgkmcnt(0)
	v_pk_add_f32 v[84:85], v[84:85], v[100:101]
	ds_bpermute_b32 v101, v130, v85
	ds_bpermute_b32 v100, v130, v84
	v_pk_add_f32 v[92:93], v[140:141], v[138:139]
	v_pk_mul_f32 v[138:139], v[74:75], v[74:75]
	v_pk_mul_f32 v[140:141], v[72:73], v[72:73]
	v_and_b32_e32 v105, 15, v122
	s_waitcnt lgkmcnt(0)
	v_pk_add_f32 v[100:101], v[84:85], v[100:101]
	v_mov_b64_e32 v[84:85], s[0:1]
	v_pk_fma_f32 v[144:145], v[100:101], s[28:29], v[84:85] op_sel_hi:[1,0,0]
	s_mov_b32 s1, 0x800000
	v_mul_f32_e32 v100, 0x4b800000, v145
	v_cmp_gt_f32_e32 vcc, s1, v145
	s_movk_i32 s0, 0x1080
	v_pk_mov_b32 v[142:143], v[140:141], v[138:139] op_sel:[1,0]
	v_cndmask_b32_e32 v100, v145, v100, vcc
	v_rsq_f32_e32 v131, v100
	v_mul_lo_u32 v138, v124, s0
	v_mov_b32_e32 v141, v139
	v_pk_add_f32 v[100:101], v[142:143], v[140:141]
	v_mul_f32_e32 v124, 0x45800000, v131
	v_cndmask_b32_e32 v124, v131, v124, vcc
	v_pk_mul_f32 v[132:133], v[132:133], v[124:125] op_sel_hi:[1,0]
	v_add3_u32 v142, s69, v104, v138
	v_pk_fma_f32 v[132:133], v[0:1], v[132:133], v[4:5]
	v_pk_mul_f32 v[102:103], v[102:103], v[124:125] op_sel_hi:[1,0]
	v_mul_f32_e32 v131, 0xbfb8aa3b, v132
	v_exp_f32_e32 v131, v131
	v_mul_f32_e32 v139, 0xbfb8aa3b, v133
	v_exp_f32_e32 v139, v139
	v_pk_fma_f32 v[102:103], v[2:3], v[102:103], v[6:7]
	v_add_f32_e32 v104, 1.0, v131
	v_rcp_f32_e32 v138, v104
	v_add_f32_e32 v104, 1.0, v139
	v_rcp_f32_e32 v139, v104
	v_mul_f32_e32 v104, 0xbfb8aa3b, v102
	v_exp_f32_e32 v104, v104
	v_mul_f32_e32 v124, 0xbfb8aa3b, v103
	v_exp_f32_e32 v124, v124
	v_mov_b32_e32 v140, v136
	v_mov_b32_e32 v141, v134
	v_mov_b32_e32 v134, v137
	v_pk_add_f32 v[134:135], v[140:141], v[134:135]
	v_add_f32_e32 v104, 1.0, v104
	ds_bpermute_b32 v137, v125, v135
	ds_bpermute_b32 v136, v125, v134
	v_pk_mul_f32 v[132:133], v[132:133], v[138:139]
	v_rcp_f32_e32 v138, v104
	v_add_f32_e32 v104, 1.0, v124
	v_rcp_f32_e32 v139, v104
	v_mul_f32_e32 v104, 0x4b800000, v144
	v_cmp_gt_f32_e32 vcc, s1, v144
	s_waitcnt lgkmcnt(0)
	v_pk_add_f32 v[134:135], v[134:135], v[136:137]
	ds_bpermute_b32 v137, v126, v135
	v_cndmask_b32_e32 v104, v144, v104, vcc
	v_rsq_f32_e32 v104, v104
	ds_bpermute_b32 v136, v126, v134
	v_pk_mul_f32 v[102:103], v[102:103], v[138:139]
	v_cvt_pk_bf16_f32 v132, v132, v133
	v_mul_f32_e32 v124, 0x45800000, v104
	v_cndmask_b32_e32 v104, v104, v124, vcc
	v_pk_mul_f32 v[120:121], v[120:121], v[104:105] op_sel_hi:[1,0]
	s_waitcnt lgkmcnt(0)
	v_pk_add_f32 v[134:135], v[134:135], v[136:137]
	v_pk_fma_f32 v[120:121], v[0:1], v[120:121], v[4:5]
	ds_bpermute_b32 v137, v127, v135
	v_mul_f32_e32 v124, 0xbfb8aa3b, v120
	ds_bpermute_b32 v136, v127, v134
	v_exp_f32_e32 v124, v124
	v_mul_f32_e32 v131, 0xbfb8aa3b, v121
	v_exp_f32_e32 v131, v131
	v_cvt_pk_bf16_f32 v133, v102, v103
	v_add_f32_e32 v124, 1.0, v124
	s_waitcnt lgkmcnt(0)
	v_pk_add_f32 v[134:135], v[134:135], v[136:137]
	v_rcp_f32_e32 v140, v124
	v_add_f32_e32 v124, 1.0, v131
	ds_bpermute_b32 v137, v128, v135
	ds_bpermute_b32 v136, v128, v134
	v_rcp_f32_e32 v141, v124
	v_pk_mul_f32 v[98:99], v[98:99], v[104:105] op_sel_hi:[1,0]
	s_ashr_i32 s40, s94, 3
	v_pk_fma_f32 v[98:99], v[2:3], v[98:99], v[6:7]
	v_pk_mul_f32 v[102:103], v[120:121], v[140:141]
	s_waitcnt lgkmcnt(0)
	v_pk_add_f32 v[120:121], v[134:135], v[136:137]
	ds_bpermute_b32 v135, v129, v121
	ds_bpermute_b32 v134, v129, v120
	v_mul_f32_e32 v104, 0xbfb8aa3b, v98
	v_exp_f32_e32 v104, v104
	v_cvt_pk_bf16_f32 v102, v102, v103
	s_lshl_b32 s3, s40, 7
	s_waitcnt lgkmcnt(0)
	v_pk_add_f32 v[120:121], v[120:121], v[134:135]
	ds_bpermute_b32 v135, v130, v121
	ds_bpermute_b32 v134, v130, v120
	v_add_f32_e32 v103, 1.0, v104
	v_mul_f32_e32 v104, 0xbfb8aa3b, v99
	v_exp_f32_e32 v104, v104
	v_readlane_b32 s44, v253, 3
	s_waitcnt lgkmcnt(0)
	v_pk_add_f32 v[120:121], v[120:121], v[134:135]
	v_rcp_f32_e32 v134, v103
	v_pk_fma_f32 v[120:121], v[120:121], s[28:29], v[84:85] op_sel_hi:[1,0,0]
	v_add_f32_e32 v103, 1.0, v104
	v_mul_f32_e32 v124, 0x4b800000, v121
	v_cmp_gt_f32_e32 vcc, s1, v121
	v_rcp_f32_e32 v135, v103
	v_readlane_b32 s52, v253, 11
	v_cndmask_b32_e32 v121, v121, v124, vcc
	v_rsq_f32_e32 v121, v121
	v_pk_mul_f32 v[98:99], v[98:99], v[134:135]
	v_readlane_b32 s53, v253, 12
	s_mul_i32 s38, s40, 0xb0000
	v_mul_f32_e32 v103, 0x45800000, v121
	v_cndmask_b32_e32 v104, v121, v103, vcc
	v_pk_mul_f32 v[116:117], v[116:117], v[104:105] op_sel_hi:[1,0]
	v_pk_mul_f32 v[94:95], v[94:95], v[104:105] op_sel_hi:[1,0]
	v_pk_fma_f32 v[116:117], v[0:1], v[116:117], v[4:5]
	v_pk_fma_f32 v[94:95], v[2:3], v[94:95], v[6:7]
	v_mul_f32_e32 v103, 0xbfb8aa3b, v116
	v_exp_f32_e32 v103, v103
	v_mul_f32_e32 v121, 0xbfb8aa3b, v117
	v_exp_f32_e32 v121, v121
	v_cmp_gt_f32_e32 vcc, s1, v120
	v_add_f32_e32 v103, 1.0, v103
	v_rcp_f32_e32 v134, v103
	v_add_f32_e32 v103, 1.0, v121
	v_rcp_f32_e32 v135, v103
	v_cvt_pk_bf16_f32 v103, v98, v99
	v_add_u32_e32 v121, 0x8000, v142
	ds_write2_b64 v121, v[132:133], v[102:103] offset1:66
	v_mul_f32_e32 v102, 0xbfb8aa3b, v94
	v_exp_f32_e32 v102, v102
	v_mul_f32_e32 v103, 0xbfb8aa3b, v95
	v_exp_f32_e32 v103, v103
	v_pk_mul_f32 v[98:99], v[116:117], v[134:135]
	v_mov_b32_e32 v116, v118
	v_mov_b32_e32 v117, v114
	v_mov_b32_e32 v114, v119
	v_cvt_pk_bf16_f32 v98, v98, v99
	v_add_f32_e32 v99, 1.0, v102
	v_pk_add_f32 v[114:115], v[116:117], v[114:115]
	v_rcp_f32_e32 v102, v99
	v_add_f32_e32 v99, 1.0, v103
	ds_bpermute_b32 v117, v125, v115
	ds_bpermute_b32 v116, v125, v114
	v_rcp_f32_e32 v103, v99
	v_mul_f32_e32 v99, 0x4b800000, v120
	v_cndmask_b32_e32 v99, v120, v99, vcc
	v_rsq_f32_e32 v104, v99
	v_pk_mul_f32 v[94:95], v[94:95], v[102:103]
	s_waitcnt lgkmcnt(0)
	v_pk_add_f32 v[102:103], v[114:115], v[116:117]
	ds_bpermute_b32 v115, v126, v103
	ds_bpermute_b32 v114, v126, v102
	v_cvt_pk_bf16_f32 v99, v94, v95
	v_mul_f32_e32 v94, 0x45800000, v104
	v_cndmask_b32_e32 v94, v104, v94, vcc
	v_pk_mul_f32 v[96:97], v[96:97], v[94:95] op_sel_hi:[1,0]
	s_waitcnt lgkmcnt(0)
	v_pk_add_f32 v[102:103], v[102:103], v[114:115]
	v_pk_fma_f32 v[96:97], v[0:1], v[96:97], v[4:5]
	ds_bpermute_b32 v115, v127, v103
	v_mul_f32_e32 v95, 0xbfb8aa3b, v96
	v_exp_f32_e32 v95, v95
	ds_bpermute_b32 v114, v127, v102
	s_mul_hi_i32 s39, s3, 0x1600
	v_readlane_b32 s45, v253, 4
	v_add_f32_e32 v95, 1.0, v95
	v_rcp_f32_e32 v116, v95
	v_mul_f32_e32 v95, 0xbfb8aa3b, v97
	s_waitcnt lgkmcnt(0)
	v_pk_add_f32 v[102:103], v[102:103], v[114:115]
	v_exp_f32_e32 v95, v95
	ds_bpermute_b32 v115, v128, v103
	ds_bpermute_b32 v114, v128, v102
	v_readlane_b32 s46, v253, 5
	v_add_f32_e32 v95, 1.0, v95
	v_rcp_f32_e32 v117, v95
	v_pk_mul_f32 v[90:91], v[90:91], v[94:95] op_sel_hi:[1,0]
	s_waitcnt lgkmcnt(0)
	v_pk_add_f32 v[94:95], v[102:103], v[114:115]
	ds_bpermute_b32 v103, v129, v95
	ds_bpermute_b32 v102, v129, v94
	v_pk_fma_f32 v[90:91], v[2:3], v[90:91], v[6:7]
	v_pk_mul_f32 v[96:97], v[96:97], v[116:117]
	v_mul_f32_e32 v104, 0xbfb8aa3b, v90
	v_exp_f32_e32 v104, v104
	s_waitcnt lgkmcnt(0)
	v_pk_add_f32 v[94:95], v[94:95], v[102:103]
	ds_bpermute_b32 v103, v130, v95
	ds_bpermute_b32 v102, v130, v94
	v_mul_f32_e32 v114, 0xbfb8aa3b, v91
	v_exp_f32_e32 v115, v114
	v_cvt_pk_bf16_f32 v96, v96, v97
	v_add_f32_e32 v104, 1.0, v104
	s_waitcnt lgkmcnt(0)
	v_pk_add_f32 v[94:95], v[94:95], v[102:103]
	v_rcp_f32_e32 v114, v104
	v_pk_fma_f32 v[94:95], v[94:95], s[28:29], v[84:85] op_sel_hi:[1,0,0]
	v_add_f32_e32 v104, 1.0, v115
	v_mul_f32_e32 v102, 0x4b800000, v95
	v_cmp_gt_f32_e32 vcc, s1, v95
	v_rcp_f32_e32 v115, v104
	v_readlane_b32 s47, v253, 6
	v_cndmask_b32_e32 v95, v95, v102, vcc
	v_rsq_f32_e32 v95, v95
	v_pk_mul_f32 v[90:91], v[90:91], v[114:115]
	v_readlane_b32 s48, v253, 7
	v_readlane_b32 s49, v253, 8
	v_mul_f32_e32 v97, 0x45800000, v95
	v_cndmask_b32_e32 v102, v95, v97, vcc
	v_pk_mul_f32 v[88:89], v[88:89], v[102:103] op_sel_hi:[1,0]
	v_cmp_gt_f32_e32 vcc, s1, v94
	v_pk_fma_f32 v[88:89], v[0:1], v[88:89], v[4:5]
	v_readlane_b32 s50, v253, 9
	v_mul_f32_e32 v95, 0xbfb8aa3b, v88
	v_mul_f32_e32 v97, 0xbfb8aa3b, v89
	v_exp_f32_e32 v95, v95
	v_exp_f32_e32 v103, v97
	v_cvt_pk_bf16_f32 v97, v90, v91
	ds_write2_b64 v121, v[98:99], v[96:97] offset0:132 offset1:198
	v_add_f32_e32 v90, 1.0, v95
	v_add_f32_e32 v91, 1.0, v103
	v_rcp_f32_e32 v90, v90
	v_rcp_f32_e32 v91, v91
	v_pk_mul_f32 v[86:87], v[86:87], v[102:103] op_sel_hi:[1,0]
	v_readlane_b32 s51, v253, 10
	v_pk_fma_f32 v[86:87], v[2:3], v[86:87], v[6:7]
	v_pk_mul_f32 v[88:89], v[88:89], v[90:91]
	v_mov_b32_e32 v90, v100
	v_mov_b32_e32 v91, v92
	v_mov_b32_e32 v92, v101
	v_pk_add_f32 v[90:91], v[90:91], v[92:93]
	ds_bpermute_b32 v93, v125, v91
	ds_bpermute_b32 v92, v125, v90
	v_cvt_pk_bf16_f32 v88, v88, v89
	v_mul_f32_e32 v89, 0x4b800000, v94
	v_mul_f32_e32 v95, 0xbfb8aa3b, v86
	v_cndmask_b32_e32 v89, v94, v89, vcc
	s_waitcnt lgkmcnt(0)
	v_pk_add_f32 v[90:91], v[90:91], v[92:93]
	ds_bpermute_b32 v93, v126, v91
	ds_bpermute_b32 v92, v126, v90
	v_exp_f32_e32 v95, v95
	v_mul_f32_e32 v102, 0xbfb8aa3b, v87
	v_rsq_f32_e32 v89, v89
	v_exp_f32_e32 v103, v102
	s_waitcnt lgkmcnt(0)
	v_pk_add_f32 v[90:91], v[90:91], v[92:93]
	v_add_f32_e32 v95, 1.0, v95
	v_mul_f32_e32 v94, 0x45800000, v89
	ds_bpermute_b32 v93, v127, v91
	ds_bpermute_b32 v92, v127, v90
	v_rcp_f32_e32 v102, v95
	v_add_f32_e32 v95, 1.0, v103
	v_cndmask_b32_e32 v94, v89, v94, vcc
	v_pk_mul_f32 v[80:81], v[80:81], v[94:95] op_sel_hi:[1,0]
	v_rcp_f32_e32 v103, v95
	v_pk_fma_f32 v[80:81], v[0:1], v[80:81], v[4:5]
	s_waitcnt lgkmcnt(0)
	v_pk_add_f32 v[90:91], v[90:91], v[92:93]
	v_mul_f32_e32 v89, 0xbfb8aa3b, v80
	v_exp_f32_e32 v89, v89
	v_mul_f32_e32 v95, 0xbfb8aa3b, v81
	v_exp_f32_e32 v95, v95
	ds_bpermute_b32 v93, v128, v91
	ds_bpermute_b32 v92, v128, v90
	v_add_f32_e32 v89, 1.0, v89
	v_pk_mul_f32 v[86:87], v[86:87], v[102:103]
	v_rcp_f32_e32 v96, v89
	v_add_f32_e32 v89, 1.0, v95
	v_rcp_f32_e32 v97, v89
	v_cvt_pk_bf16_f32 v89, v86, v87
	s_waitcnt lgkmcnt(0)
	v_pk_add_f32 v[86:87], v[90:91], v[92:93]
	ds_bpermute_b32 v91, v129, v87
	ds_bpermute_b32 v90, v129, v86
	v_pk_mul_f32 v[82:83], v[82:83], v[94:95] op_sel_hi:[1,0]
	v_pk_mul_f32 v[80:81], v[80:81], v[96:97]
	v_pk_fma_f32 v[82:83], v[2:3], v[82:83], v[6:7]
	v_cvt_pk_bf16_f32 v80, v80, v81
	s_waitcnt lgkmcnt(0)
	v_pk_add_f32 v[86:87], v[86:87], v[90:91]
	ds_bpermute_b32 v91, v130, v87
	ds_bpermute_b32 v90, v130, v86
	v_mul_f32_e32 v92, 0xbfb8aa3b, v82
	v_mul_f32_e32 v93, 0xbfb8aa3b, v83
	v_exp_f32_e32 v92, v92
	v_exp_f32_e32 v93, v93
	s_waitcnt lgkmcnt(0)
	v_pk_add_f32 v[86:87], v[86:87], v[90:91]
	v_add_u32_e32 v90, 0x8800, v142
	v_pk_fma_f32 v[84:85], v[86:87], s[28:29], v[84:85] op_sel_hi:[1,0,0]
	v_add_f32_e32 v92, 1.0, v92
	v_add_f32_e32 v93, 1.0, v93
	v_mul_f32_e32 v86, 0x4b800000, v85
	v_cmp_gt_f32_e32 vcc, s1, v85
	v_rcp_f32_e32 v92, v92
	v_rcp_f32_e32 v93, v93
	v_cndmask_b32_e32 v85, v85, v86, vcc
	v_rsq_f32_e32 v85, v85
	v_readlane_b32 s54, v253, 13
	v_pk_mul_f32 v[82:83], v[82:83], v[92:93]
	v_readlane_b32 s55, v253, 14
	v_cvt_pk_bf16_f32 v81, v82, v83
	v_mul_f32_e32 v82, 0x45800000, v85
	v_cndmask_b32_e32 v82, v85, v82, vcc
	v_pk_mul_f32 v[76:77], v[76:77], v[82:83] op_sel_hi:[1,0]
	ds_write2_b64 v90, v[88:89], v[80:81] offset0:8 offset1:74
	v_pk_fma_f32 v[76:77], v[0:1], v[76:77], v[4:5]
	v_cmp_gt_f32_e32 vcc, s1, v84
	v_mul_f32_e32 v83, 0xbfb8aa3b, v76
	v_exp_f32_e32 v83, v83
	v_mul_f32_e32 v85, 0xbfb8aa3b, v77
	v_exp_f32_e32 v85, v85
	v_readlane_b32 s56, v253, 15
	v_add_f32_e32 v83, 1.0, v83
	v_rcp_f32_e32 v86, v83
	v_add_f32_e32 v83, 1.0, v85
	v_pk_mul_f32 v[78:79], v[78:79], v[82:83] op_sel_hi:[1,0]
	v_rcp_f32_e32 v87, v83
	v_pk_fma_f32 v[78:79], v[2:3], v[78:79], v[6:7]
	v_readlane_b32 s57, v253, 16
	v_mul_f32_e32 v82, 0xbfb8aa3b, v78
	v_exp_f32_e32 v82, v82
	v_mul_f32_e32 v80, 0xbfb8aa3b, v79
	v_exp_f32_e32 v81, v80
	v_mul_f32_e32 v80, 0x4b800000, v84
	v_pk_mul_f32 v[76:77], v[76:77], v[86:87]
	v_cndmask_b32_e32 v80, v84, v80, vcc
	v_cvt_pk_bf16_f32 v76, v76, v77
	v_add_f32_e32 v77, 1.0, v82
	v_rsq_f32_e32 v82, v80
	v_rcp_f32_e32 v80, v77
	v_add_f32_e32 v77, 1.0, v81
	v_rcp_f32_e32 v81, v77
	v_mul_f32_e32 v77, 0x45800000, v82
	v_cndmask_b32_e32 v82, v82, v77, vcc
	v_pk_mul_f32 v[72:73], v[72:73], v[82:83] op_sel_hi:[1,0]
	v_pk_mul_f32 v[74:75], v[74:75], v[82:83] op_sel_hi:[1,0]
	v_pk_fma_f32 v[0:1], v[0:1], v[72:73], v[4:5]
	v_pk_fma_f32 v[2:3], v[2:3], v[74:75], v[6:7]
	v_mul_f32_e32 v4, 0xbfb8aa3b, v0
	v_exp_f32_e32 v72, v4
	v_mul_f32_e32 v4, 0xbfb8aa3b, v1
	v_mul_f32_e32 v6, 0xbfb8aa3b, v2
	v_mul_f32_e32 v7, 0xbfb8aa3b, v3
	v_exp_f32_e32 v73, v4
	v_exp_f32_e32 v6, v6
	v_exp_f32_e32 v7, v7
	v_add_f32_e32 v72, 1.0, v72
	v_add_f32_e32 v73, 1.0, v73
	v_add_f32_e32 v6, 1.0, v6
	v_add_f32_e32 v7, 1.0, v7
	v_rcp_f32_e32 v72, v72
	v_rcp_f32_e32 v73, v73
	v_rcp_f32_e32 v6, v6
	v_rcp_f32_e32 v7, v7
	v_pk_mul_f32 v[4:5], v[78:79], v[80:81]
	v_pk_mul_f32 v[0:1], v[0:1], v[72:73]
	v_cvt_pk_bf16_f32 v77, v4, v5
	v_pk_mul_f32 v[2:3], v[2:3], v[6:7]
	v_cvt_pk_bf16_f32 v0, v0, v1
	v_cvt_pk_bf16_f32 v1, v2, v3
	ds_write2_b64 v90, v[76:77], v[0:1] offset0:140 offset1:206
	v_and_b32_e32 v0, 48, v122
	v_mul_u32_u24_e32 v1, 0x210, v105
	s_waitcnt lgkmcnt(0)
	s_barrier
	v_add3_u32 v92, s69, v0, v1
	ds_read_b128 v[0:3], v92 offset:32768
	ds_read_b128 v[4:7], v92 offset:32832
	ds_read_b128 v[84:87], v92 offset:41216
	ds_read_b128 v[88:91], v92 offset:41280
	s_waitcnt vmcnt(15) lgkmcnt(3)
	v_mfma_f32_16x16x32_bf16 v[72:75], v[0:3], v[56:59], 0
	v_readlane_b32 s58, v253, 17
	v_readlane_b32 s59, v253, 18
	s_waitcnt vmcnt(13)
	v_mfma_f32_16x16x32_bf16 v[76:79], v[0:3], v[60:63], 0
	s_waitcnt vmcnt(11)
	v_mfma_f32_16x16x32_bf16 v[80:83], v[0:3], v[64:67], 0
	s_waitcnt vmcnt(9)
	v_mfma_f32_16x16x32_bf16 v[0:3], v[0:3], v[68:71], 0
	s_waitcnt lgkmcnt(1)
	v_mfma_f32_16x16x32_bf16 v[56:59], v[84:87], v[56:59], 0
	v_mfma_f32_16x16x32_bf16 v[60:63], v[84:87], v[60:63], 0
	v_mfma_f32_16x16x32_bf16 v[64:67], v[84:87], v[64:67], 0
	v_mfma_f32_16x16x32_bf16 v[68:71], v[84:87], v[68:71], 0
	v_mfma_f32_16x16x32_bf16 v[72:75], v[4:7], v[40:43], v[72:75]
	v_mfma_f32_16x16x32_bf16 v[76:79], v[4:7], v[44:47], v[76:79]
	v_mfma_f32_16x16x32_bf16 v[80:83], v[4:7], v[48:51], v[80:83]
	s_waitcnt vmcnt(8)
	v_mfma_f32_16x16x32_bf16 v[0:3], v[4:7], v[52:55], v[0:3]
	s_waitcnt lgkmcnt(0)
	v_mfma_f32_16x16x32_bf16 v[4:7], v[88:91], v[40:43], v[56:59]
	v_mfma_f32_16x16x32_bf16 v[40:43], v[88:91], v[44:47], v[60:63]
	v_mfma_f32_16x16x32_bf16 v[44:47], v[88:91], v[48:51], v[64:67]
	v_mfma_f32_16x16x32_bf16 v[48:51], v[88:91], v[52:55], v[68:71]
	ds_read_b128 v[52:55], v92 offset:32896
	ds_read_b128 v[56:59], v92 offset:32960
	s_waitcnt vmcnt(7) lgkmcnt(1)
	v_mfma_f32_16x16x32_bf16 v[60:63], v[52:55], v[24:27], v[72:75]
	s_waitcnt vmcnt(5)
	v_mfma_f32_16x16x32_bf16 v[64:67], v[52:55], v[28:31], v[76:79]
	s_waitcnt vmcnt(3)
	v_mfma_f32_16x16x32_bf16 v[68:71], v[52:55], v[32:35], v[80:83]
	s_waitcnt vmcnt(1)
	v_mfma_f32_16x16x32_bf16 v[0:3], v[52:55], v[36:39], v[0:3]
	ds_read_b128 v[52:55], v92 offset:41344
	ds_read_b128 v[72:75], v92 offset:41408
	s_waitcnt lgkmcnt(1)
	v_mfma_f32_16x16x32_bf16 v[4:7], v[52:55], v[24:27], v[4:7]
	v_mfma_f32_16x16x32_bf16 v[24:27], v[52:55], v[28:31], v[40:43]
	v_mfma_f32_16x16x32_bf16 v[28:31], v[52:55], v[32:35], v[44:47]
	s_nop 2
	v_lshl_add_u64 v[44:45], s[86:87], 0, v[106:107]
	v_mfma_f32_16x16x32_bf16 v[32:35], v[52:55], v[36:39], v[48:51]
	v_lshl_add_u64 v[76:77], v[44:45], 0, v[200:201]
	v_lshl_add_u64 v[52:53], s[86:87], 0, v[110:111]
	v_lshl_add_u64 v[78:79], v[52:53], 0, v[200:201]
	v_mfma_f32_16x16x32_bf16 v[36:39], v[56:59], v[20:23], v[60:63]
	global_load_dwordx4 v[48:51], v[76:77], off offset:256
	global_load_dwordx4 v[52:55], v[78:79], off offset:256
	s_nop 0
	global_load_dwordx4 v[60:63], v[78:79], off offset:320
	v_mfma_f32_16x16x32_bf16 v[40:43], v[56:59], v[12:15], v[64:67]
	v_mfma_f32_16x16x32_bf16 v[44:47], v[56:59], v[16:19], v[68:71]
	s_waitcnt vmcnt(3)
	v_mfma_f32_16x16x32_bf16 v[0:3], v[56:59], v[8:11], v[0:3]
	v_lshl_add_u64 v[56:57], s[86:87], 0, v[112:113]
	v_lshl_add_u64 v[80:81], v[56:57], 0, v[200:201]
	v_lshl_add_u64 v[56:57], s[86:87], 0, v[108:109]
	v_lshl_add_u64 v[82:83], v[56:57], 0, v[200:201]
	s_waitcnt lgkmcnt(0)
	v_mfma_f32_16x16x32_bf16 v[4:7], v[72:75], v[20:23], v[4:7]
	global_load_dwordx4 v[20:23], v[80:81], off offset:256
	global_load_dwordx4 v[64:67], v[80:81], off offset:320
	global_load_dwordx4 v[68:71], v[82:83], off offset:320
	v_mfma_f32_16x16x32_bf16 v[12:15], v[72:75], v[12:15], v[24:27]
	ds_read_b128 v[56:59], v92 offset:33088
	v_lshlrev_b32_e32 v200, 1, v105
	s_nop 0
	global_load_dwordx4 v[24:27], v[82:83], off offset:256
	v_mfma_f32_16x16x32_bf16 v[8:11], v[72:75], v[8:11], v[32:35]
	s_nop 2
	global_load_dwordx4 v[32:35], v[76:77], off offset:320
	v_mfma_f32_16x16x32_bf16 v[16:19], v[72:75], v[16:19], v[28:31]
	s_nop 2
	ds_read_b128 v[28:31], v92 offset:33024
	s_waitcnt vmcnt(7) lgkmcnt(0)
	v_mfma_f32_16x16x32_bf16 v[36:39], v[28:31], v[48:51], v[36:39]
	s_waitcnt vmcnt(6)
	v_mfma_f32_16x16x32_bf16 v[40:43], v[28:31], v[52:55], v[40:43]
	s_waitcnt vmcnt(4)
	v_mfma_f32_16x16x32_bf16 v[44:47], v[28:31], v[20:23], v[44:47]
	s_waitcnt vmcnt(1)
	v_mfma_f32_16x16x32_bf16 v[0:3], v[28:31], v[24:27], v[0:3]
	ds_read_b128 v[28:31], v92 offset:41472
	ds_read_b128 v[72:75], v92 offset:41536
	s_waitcnt lgkmcnt(1)
	v_mfma_f32_16x16x32_bf16 v[4:7], v[28:31], v[48:51], v[4:7]
	ds_read_b128 v[48:51], v92 offset:33152
	v_mfma_f32_16x16x32_bf16 v[12:15], v[28:31], v[52:55], v[12:15]
	global_load_dwordx4 v[52:55], v[76:77], off offset:448
	v_mfma_f32_16x16x32_bf16 v[16:19], v[28:31], v[20:23], v[16:19]
	v_mfma_f32_16x16x32_bf16 v[8:11], v[28:31], v[24:27], v[8:11]
	s_waitcnt vmcnt(1)
	v_mfma_f32_16x16x32_bf16 v[20:23], v[56:59], v[32:35], v[36:39]
	v_mfma_f32_16x16x32_bf16 v[24:27], v[56:59], v[60:63], v[40:43]
	s_nop 1
	global_load_dwordx4 v[36:39], v[76:77], off offset:384
	v_mfma_f32_16x16x32_bf16 v[28:31], v[56:59], v[64:67], v[44:47]
	global_load_dwordx4 v[40:43], v[78:79], off offset:384
	s_waitcnt lgkmcnt(1)
	v_mfma_f32_16x16x32_bf16 v[4:7], v[72:75], v[32:35], v[4:7]
	global_load_dwordx4 v[32:35], v[80:81], off offset:384
	global_load_dwordx4 v[44:47], v[82:83], off offset:384
	v_mfma_f32_16x16x32_bf16 v[12:15], v[72:75], v[60:63], v[12:15]
	global_load_dwordx4 v[60:63], v[78:79], off offset:448
	v_mfma_f32_16x16x32_bf16 v[0:3], v[56:59], v[68:71], v[0:3]
	ds_read_b128 v[56:59], v92 offset:33216
	v_mfma_f32_16x16x32_bf16 v[16:19], v[72:75], v[64:67], v[16:19]
	global_load_dwordx4 v[64:67], v[80:81], off offset:448
	v_mfma_f32_16x16x32_bf16 v[8:11], v[72:75], v[68:71], v[8:11]
	global_load_dwordx4 v[68:71], v[82:83], off offset:448
	s_waitcnt vmcnt(6) lgkmcnt(1)
	v_mfma_f32_16x16x32_bf16 v[20:23], v[48:51], v[36:39], v[20:23]
	s_waitcnt vmcnt(5)
	v_mfma_f32_16x16x32_bf16 v[24:27], v[48:51], v[40:43], v[24:27]
	s_waitcnt vmcnt(4)
	v_mfma_f32_16x16x32_bf16 v[28:31], v[48:51], v[32:35], v[28:31]
	s_waitcnt vmcnt(3)
	v_mfma_f32_16x16x32_bf16 v[0:3], v[48:51], v[44:47], v[0:3]
	ds_read_b128 v[48:51], v92 offset:41600
	ds_read_b128 v[72:75], v92 offset:41664
	s_waitcnt lgkmcnt(1)
	v_mfma_f32_16x16x32_bf16 v[16:19], v[48:51], v[32:35], v[16:19]
	v_lshrrev_b32_e32 v32, 2, v123
	v_and_b32_e32 v34, 0xffffffc0, v122
	v_and_or_b32 v32, v32, 12, s2
	v_mfma_f32_16x16x32_bf16 v[20:23], v[56:59], v[52:55], v[20:23]
	v_ashrrev_i32_e32 v35, 31, v34
	v_lshl_add_u64 v[34:35], v[34:35], 1, s[22:23]
	v_ashrrev_i32_e32 v33, 31, v32
	s_waitcnt vmcnt(2)
	v_mfma_f32_16x16x32_bf16 v[24:27], v[56:59], v[60:63], v[24:27]
	v_lshl_add_u64 v[34:35], v[34:35], 0, v[200:201]
	s_nop 1
	v_cvt_pk_bf16_f32 v20, v20, s0
	s_bfe_u32 s2, s94, 0x20001
	s_waitcnt vmcnt(1)
	v_mfma_f32_16x16x32_bf16 v[28:31], v[56:59], v[64:67], v[28:31]
	s_cmp_gt_i32 s40, 31
	s_waitcnt vmcnt(0)
	v_mfma_f32_16x16x32_bf16 v[0:3], v[56:59], v[68:71], v[0:3]
	v_mfma_f32_16x16x32_bf16 v[4:7], v[48:51], v[36:39], v[4:7]
	v_lshlrev_b64 v[36:37], 11, v[32:33]
	v_lshl_add_u64 v[36:37], v[34:35], 0, v[36:37]
	global_store_short v[36:37], v20, off
	v_cvt_pk_bf16_f32 v20, v24, s0
	global_store_short v[36:37], v20, off offset:32
	v_cvt_pk_bf16_f32 v20, v28, s0
	s_nop 0
	v_cvt_pk_bf16_f32 v0, v0, s0
	global_store_short v[36:37], v20, off offset:64
	global_store_short v[36:37], v0, off offset:96
	v_or_b32_e32 v36, 1, v32
	v_ashrrev_i32_e32 v37, 31, v36
	v_lshlrev_b64 v[36:37], 11, v[36:37]
	v_lshl_add_u64 v[36:37], v[34:35], 0, v[36:37]
	v_cvt_pk_bf16_f32 v0, v21, s0
	global_store_short v[36:37], v0, off
	v_cvt_pk_bf16_f32 v0, v25, s0
	global_store_short v[36:37], v0, off offset:32
	v_cvt_pk_bf16_f32 v0, v29, s0
	global_store_short v[36:37], v0, off offset:64
	v_cvt_pk_bf16_f32 v0, v1, s0
	global_store_short v[36:37], v0, off offset:96
	v_or_b32_e32 v0, 2, v32
	v_ashrrev_i32_e32 v1, 31, v0
	v_lshlrev_b64 v[0:1], 11, v[0:1]
	v_lshl_add_u64 v[0:1], v[34:35], 0, v[0:1]
	v_cvt_pk_bf16_f32 v20, v22, s0
	global_store_short v[0:1], v20, off
	v_cvt_pk_bf16_f32 v20, v26, s0
	global_store_short v[0:1], v20, off offset:32
	v_cvt_pk_bf16_f32 v20, v30, s0
	v_cvt_pk_bf16_f32 v2, v2, s0
	global_store_short v[0:1], v20, off offset:64
	global_store_short v[0:1], v2, off offset:96
	v_or_b32_e32 v0, 3, v32
	v_ashrrev_i32_e32 v1, 31, v0
	v_lshlrev_b64 v[0:1], 11, v[0:1]
	v_mfma_f32_16x16x32_bf16 v[12:15], v[48:51], v[40:43], v[12:15]
	v_lshl_add_u64 v[0:1], v[34:35], 0, v[0:1]
	v_cvt_pk_bf16_f32 v2, v23, s0
	global_store_short v[0:1], v2, off
	v_cvt_pk_bf16_f32 v2, v27, s0
	v_mfma_f32_16x16x32_bf16 v[8:11], v[48:51], v[44:47], v[8:11]
	global_store_short v[0:1], v2, off offset:32
	v_cvt_pk_bf16_f32 v2, v31, s0
	global_store_short v[0:1], v2, off offset:64
	s_waitcnt lgkmcnt(0)
	v_mfma_f32_16x16x32_bf16 v[4:7], v[72:75], v[52:55], v[4:7]
	v_cvt_pk_bf16_f32 v2, v3, s0
	global_store_short v[0:1], v2, off offset:96
	v_or_b32_e32 v0, 16, v32
	v_mfma_f32_16x16x32_bf16 v[12:15], v[72:75], v[60:63], v[12:15]
	v_ashrrev_i32_e32 v1, 31, v0
	v_lshlrev_b64 v[0:1], 11, v[0:1]
	v_lshl_add_u64 v[0:1], v[34:35], 0, v[0:1]
	v_mfma_f32_16x16x32_bf16 v[16:19], v[72:75], v[64:67], v[16:19]
	v_cvt_pk_bf16_f32 v2, v4, s0
	global_store_short v[0:1], v2, off
	s_nop 1
	v_cvt_pk_bf16_f32 v2, v12, s0
	v_mfma_f32_16x16x32_bf16 v[8:11], v[72:75], v[68:71], v[8:11]
	global_store_short v[0:1], v2, off offset:32
	s_nop 0
	v_cvt_pk_bf16_f32 v2, v16, s0
	global_store_short v[0:1], v2, off offset:64
	v_mov_b32_e32 v38, v229
	v_mov_b32_e32 v22, v229
	s_nop 1
	v_cvt_pk_bf16_f32 v2, v8, s0
	global_store_short v[0:1], v2, off offset:96
	v_or_b32_e32 v0, 17, v32
	v_ashrrev_i32_e32 v1, 31, v0
	v_lshlrev_b64 v[0:1], 11, v[0:1]
	v_lshl_add_u64 v[0:1], v[34:35], 0, v[0:1]
	v_cvt_pk_bf16_f32 v2, v5, s0
	global_store_short v[0:1], v2, off
	v_cvt_pk_bf16_f32 v2, v13, s0
	global_store_short v[0:1], v2, off offset:32
	v_cvt_pk_bf16_f32 v2, v17, s0
	global_store_short v[0:1], v2, off offset:64
	v_cvt_pk_bf16_f32 v2, v9, s0
	global_store_short v[0:1], v2, off offset:96
	v_or_b32_e32 v0, 18, v32
	v_ashrrev_i32_e32 v1, 31, v0
	v_lshlrev_b64 v[0:1], 11, v[0:1]
	v_lshl_add_u64 v[0:1], v[34:35], 0, v[0:1]
	v_cvt_pk_bf16_f32 v2, v6, s0
	global_store_short v[0:1], v2, off
	v_cvt_pk_bf16_f32 v2, v14, s0
	global_store_short v[0:1], v2, off offset:32
	v_cvt_pk_bf16_f32 v2, v18, s0
	global_store_short v[0:1], v2, off offset:64
	v_cvt_pk_bf16_f32 v2, v10, s0
	global_store_short v[0:1], v2, off offset:96
	v_or_b32_e32 v0, 19, v32
	v_ashrrev_i32_e32 v1, 31, v0
	v_lshlrev_b64 v[0:1], 11, v[0:1]
	v_lshl_add_u64 v[0:1], v[34:35], 0, v[0:1]
	v_cvt_pk_bf16_f32 v2, v7, s0
	global_store_short v[0:1], v2, off
	v_cvt_pk_bf16_f32 v2, v15, s0
	global_store_short v[0:1], v2, off offset:32
	v_cvt_pk_bf16_f32 v2, v19, s0
	global_store_short v[0:1], v2, off offset:64
	v_cvt_pk_bf16_f32 v2, v11, s0
	s_cselect_b64 s[0:1], -1, 0
	s_or_b32 s28, s2, s79
	s_ashr_i32 s29, s28, 31
	s_lshl_b64 s[28:29], s[28:29], 2
	s_add_u32 s28, s52, s28
	s_addc_u32 s29, s53, s29
	global_store_short v[0:1], v2, off offset:96
	s_add_u32 s38, s20, s38
	s_waitcnt lgkmcnt(0)
	s_barrier
	s_addc_u32 s39, s21, s39
	s_lshl_b32 s41, s2, 7
	global_load_dword v41, v201, s[28:29]
	s_add_u32 s38, s38, s41
	v_lshlrev_b32_e32 v0, 2, v22
	v_and_b32_e32 v23, 60, v0
	s_addc_u32 s39, s39, 0
	v_lshlrev_b32_e32 v200, 1, v23
	v_lshl_add_u64 v[0:1], s[38:39], 0, v[200:201]
	s_mov_b64 s[28:29], 0x1200
	v_lshl_add_u64 v[0:1], v[0:1], 0, s[28:29]
	v_ashrrev_i32_e32 v2, 4, v22
	v_mad_i64_i32 v[2:3], s[28:29], v2, s92, v[0:1]
	global_load_dwordx2 v[2:3], v[2:3], off
	v_add_u32_e32 v24, 0x100, v22
	v_ashrrev_i32_e32 v4, 4, v24
	v_mad_i64_i32 v[4:5], s[28:29], v4, s92, v[0:1]
	global_load_dwordx2 v[4:5], v[4:5], off
	v_add_u32_e32 v25, 0x200, v22
	v_ashrrev_i32_e32 v6, 4, v25
	v_mad_i64_i32 v[6:7], s[28:29], v6, s92, v[0:1]
	global_load_dwordx2 v[6:7], v[6:7], off
	v_add_u32_e32 v26, 0x300, v22
	v_ashrrev_i32_e32 v8, 4, v26
	v_mad_i64_i32 v[8:9], s[28:29], v8, s92, v[0:1]
	global_load_dwordx2 v[8:9], v[8:9], off
	v_add_u32_e32 v27, 0x400, v22
	v_ashrrev_i32_e32 v10, 4, v27
	v_mad_i64_i32 v[10:11], s[28:29], v10, s92, v[0:1]
	global_load_dwordx2 v[10:11], v[10:11], off
	v_add_u32_e32 v28, 0x500, v22
	s_lshl_b32 s38, s80, 1
	v_ashrrev_i32_e32 v12, 4, v28
	s_or_b32 s28, s41, s38
	v_mad_i64_i32 v[12:13], s[38:39], v12, s92, v[0:1]
	s_add_u32 s28, s20, s28
	global_load_dwordx2 v[12:13], v[12:13], off
	v_add_u32_e32 v29, 0x600, v22
	v_add_u32_e32 v30, 0x700, v22
	v_bfe_u32 v31, v38, 2, 1
	s_addc_u32 s29, s21, 0
	v_ashrrev_i32_e32 v14, 4, v29
	v_ashrrev_i32_e32 v16, 4, v30
	v_lshlrev_b32_e32 v200, 6, v31
	v_lshlrev_b32_e32 v39, 3, v38
	v_mad_i64_i32 v[14:15], s[38:39], v14, s92, v[0:1]
	v_mad_i64_i32 v[0:1], s[38:39], v16, s92, v[0:1]
	v_lshl_add_u64 v[16:17], s[28:29], 0, v[200:201]
	v_and_b32_e32 v200, 24, v39
	v_ashrrev_i32_e32 v40, 3, v38
	global_load_dwordx2 v[14:15], v[14:15], off
	v_lshl_add_u64 v[16:17], v[16:17], 0, v[200:201]
	v_add_u32_e32 v18, s3, v40
	v_mad_i64_i32 v[18:19], s[28:29], v18, s92, v[16:17]
	global_load_dwordx2 v[0:1], v[0:1], off
	s_nop 0
	global_load_dwordx2 v[20:21], v[18:19], off
	s_nop 0
	global_load_dwordx2 v[18:19], v[18:19], off offset:32
	v_mov_b32_e32 v32, s69
	s_movk_i32 s38, 0x110
	v_ashrrev_i32_e32 v22, 3, v22
	v_mad_u32_u24 v23, v23, s38, v32
	v_and_b32_e32 v22, -2, v22
	v_add_u32_e32 v22, v23, v22
	s_waitcnt vmcnt(9)
	ds_write_b16 v22, v2 offset:17408
	ds_write_b16_d16_hi v22, v2 offset:17680
	ds_write_b16 v22, v3 offset:17952
	ds_write_b16_d16_hi v22, v3 offset:18224
	v_ashrrev_i32_e32 v2, 3, v24
	v_and_b32_e32 v2, -2, v2
	v_add_u32_e32 v2, v23, v2
	s_waitcnt vmcnt(8)
	ds_write_b16 v2, v4 offset:17408
	ds_write_b16_d16_hi v2, v4 offset:17680
	ds_write_b16 v2, v5 offset:17952
	ds_write_b16_d16_hi v2, v5 offset:18224
	v_ashrrev_i32_e32 v2, 3, v25
	v_and_b32_e32 v2, -2, v2
	v_add_u32_e32 v2, v23, v2
	s_waitcnt vmcnt(7)
	ds_write_b16 v2, v6 offset:17408
	ds_write_b16_d16_hi v2, v6 offset:17680
	ds_write_b16 v2, v7 offset:17952
	ds_write_b16_d16_hi v2, v7 offset:18224
	v_ashrrev_i32_e32 v2, 3, v26
	v_and_b32_e32 v2, -2, v2
	v_add_u32_e32 v2, v23, v2
	s_waitcnt vmcnt(6)
	ds_write_b16 v2, v8 offset:17408
	ds_write_b16_d16_hi v2, v8 offset:17680
	ds_write_b16 v2, v9 offset:17952
	ds_write_b16_d16_hi v2, v9 offset:18224
	v_ashrrev_i32_e32 v2, 3, v27
	v_and_b32_e32 v2, -2, v2
	v_add_u32_e32 v2, v23, v2
	s_waitcnt vmcnt(5)
	ds_write_b16 v2, v10 offset:17408
	ds_write_b16_d16_hi v2, v10 offset:17680
	ds_write_b16 v2, v11 offset:17952
	ds_write_b16_d16_hi v2, v11 offset:18224
	v_ashrrev_i32_e32 v2, 3, v28
	v_and_b32_e32 v2, -2, v2
	v_add_u32_e32 v2, v23, v2
	s_waitcnt vmcnt(4)
	ds_write_b16 v2, v12 offset:17408
	ds_write_b16_d16_hi v2, v12 offset:17680
	ds_write_b16 v2, v13 offset:17952
	ds_write_b16_d16_hi v2, v13 offset:18224
	v_ashrrev_i32_e32 v2, 3, v29
	s_cmp_lt_i32 s40, 32
	v_and_b32_e32 v2, -2, v2
	s_cselect_b64 s[28:29], -1, 0
	v_add_u32_e32 v2, v23, v2
	s_waitcnt vmcnt(3)
	ds_write_b16 v2, v14 offset:17408
	ds_write_b16_d16_hi v2, v14 offset:17680
	ds_write_b16 v2, v15 offset:17952
	ds_write_b16_d16_hi v2, v15 offset:18224
	v_ashrrev_i32_e32 v2, 3, v30
	s_and_b64 vcc, s[28:29], exec
	s_mov_b32 s28, 0x80000380
	v_and_b32_e32 v2, -2, v2
	s_cselect_b32 s28, 0x80, s28
	v_add_u32_e32 v2, v23, v2
	v_cmp_eq_u32_e64 s[38:39], 0, v31
	s_and_b32 s28, s28, s3
	s_waitcnt vmcnt(1)
	v_lshlrev_b32_e32 v12, 16, v20
	v_and_b32_e32 v13, 0xffff0000, v20
	v_lshlrev_b32_e32 v15, 16, v21
	s_waitcnt vmcnt(0)
	v_lshlrev_b32_e32 v8, 16, v18
	v_and_b32_e32 v9, 0xffff0000, v18
	v_lshlrev_b32_e32 v14, 16, v19
	v_and_b32_e32 v11, 0xffff0000, v19
	v_and_b32_e32 v10, 0xffff0000, v21
	s_mov_b64 s[40:41], -1
	ds_write_b16 v2, v0 offset:17408
	ds_write_b16_d16_hi v2, v0 offset:17680
	ds_write_b16 v2, v1 offset:17952
	ds_write_b16_d16_hi v2, v1 offset:18224
	v_add_u32_e32 v54, 0x100, v38
	v_ashrrev_i32_e32 v42, 3, v54
	v_add_u32_e32 v46, s3, v42
	v_mad_i64_i32 v[48:49], vcc, v46, s92, v[16:17]
	global_load_dwordx2 v[60:61], v[48:49], off
	global_load_dwordx2 v[62:63], v[48:49], off offset:32
	v_add_u32_e32 v55, 0x200, v38
	v_ashrrev_i32_e32 v43, 3, v55
	v_add_u32_e32 v46, s3, v43
	v_mad_i64_i32 v[48:49], vcc, v46, s92, v[16:17]
	global_load_dwordx2 v[64:65], v[48:49], off
	global_load_dwordx2 v[66:67], v[48:49], off offset:32
	v_add_u32_e32 v56, 0x300, v38
	v_ashrrev_i32_e32 v44, 3, v56
	v_add_u32_e32 v46, s3, v44
	v_mad_i64_i32 v[48:49], vcc, v46, s92, v[16:17]
	global_load_dwordx2 v[68:69], v[48:49], off
	global_load_dwordx2 v[70:71], v[48:49], off offset:32
	s_and_b64 vcc, exec, s[0:1]
	s_cbranch_vccz .Lkv_norot_b
	v_add_u32_e32 v32, s28, v40
	v_ashrrev_i32_e32 v32, 6, v32
	v_bfe_u32 v33, v38, 3, 6
	v_cndmask_b32_e64 v32, v33, v32, s[38:39]
	v_lshl_or_b32 v32, v32, 5, v200
	v_lshlrev_b32_e32 v50, 2, v32
	global_load_dwordx4 v[72:75], v50, s[12:13]
	global_load_dwordx4 v[76:79], v50, s[12:13] offset:16
	v_add_u32_e32 v32, s28, v42
	v_ashrrev_i32_e32 v32, 6, v32
	v_bfe_u32 v33, v54, 3, 6
	v_cndmask_b32_e64 v32, v33, v32, s[38:39]
	v_lshl_or_b32 v32, v32, 5, v200
	v_lshlrev_b32_e32 v51, 2, v32
	global_load_dwordx4 v[80:83], v51, s[12:13]
	global_load_dwordx4 v[84:87], v51, s[12:13] offset:16
	v_add_u32_e32 v32, s28, v43
	v_ashrrev_i32_e32 v32, 6, v32
	v_bfe_u32 v33, v55, 3, 6
	v_cndmask_b32_e64 v32, v33, v32, s[38:39]
	v_lshl_or_b32 v32, v32, 5, v200
	v_lshlrev_b32_e32 v52, 2, v32
	global_load_dwordx4 v[88:91], v52, s[12:13]
	global_load_dwordx4 v[92:95], v52, s[12:13] offset:16
	v_add_u32_e32 v32, s28, v44
	v_ashrrev_i32_e32 v32, 6, v32
	v_bfe_u32 v33, v56, 3, 6
	v_cndmask_b32_e64 v32, v33, v32, s[38:39]
	v_lshl_or_b32 v32, v32, 5, v200
	v_lshlrev_b32_e32 v53, 2, v32
	global_load_dwordx4 v[96:99], v53, s[12:13]
	global_load_dwordx4 v[100:103], v53, s[12:13] offset:16
	s_waitcnt vmcnt(0)
	v_mul_f32_e32 v34, v8, v73
	v_mul_f32_e32 v35, v12, v73
	v_fma_f32 v0, v12, v72, -v34
	v_fma_f32 v6, v8, v72, v35
	v_mul_f32_e32 v34, v9, v75
	v_mul_f32_e32 v35, v13, v75
	v_fma_f32 v1, v13, v74, -v34
	v_fma_f32 v7, v9, v74, v35
	v_mul_f32_e32 v34, v14, v77
	v_mul_f32_e32 v35, v15, v77
	v_fma_f32 v2, v15, v76, -v34
	v_fma_f32 v4, v14, v76, v35
	v_mul_f32_e32 v34, v11, v79
	v_mul_f32_e32 v35, v10, v79
	v_fma_f32 v3, v10, v78, -v34
	v_fma_f32 v5, v11, v78, v35
	v_lshlrev_b32_e32 v32, 16, v60
	v_lshlrev_b32_e32 v33, 16, v62
	v_mul_f32_e32 v34, v33, v81
	v_mul_f32_e32 v35, v32, v81
	v_fma_f32 v8, v32, v80, -v34
	v_fma_f32 v14, v33, v80, v35
	v_and_b32_e32 v32, 0xffff0000, v60
	v_and_b32_e32 v33, 0xffff0000, v62
	v_mul_f32_e32 v34, v33, v83
	v_mul_f32_e32 v35, v32, v83
	v_fma_f32 v9, v32, v82, -v34
	v_fma_f32 v15, v33, v82, v35
	v_lshlrev_b32_e32 v32, 16, v61
	v_lshlrev_b32_e32 v33, 16, v63
	v_mul_f32_e32 v34, v33, v85
	v_mul_f32_e32 v35, v32, v85
	v_fma_f32 v10, v32, v84, -v34
	v_fma_f32 v12, v33, v84, v35
	v_and_b32_e32 v32, 0xffff0000, v61
	v_and_b32_e32 v33, 0xffff0000, v63
	v_mul_f32_e32 v34, v33, v87
	v_mul_f32_e32 v35, v32, v87
	v_fma_f32 v11, v32, v86, -v34
	v_fma_f32 v13, v33, v86, v35
	v_lshlrev_b32_e32 v32, 16, v64
	v_lshlrev_b32_e32 v33, 16, v66
	v_mul_f32_e32 v34, v33, v89
	v_mul_f32_e32 v35, v32, v89
	v_fma_f32 v18, v32, v88, -v34
	v_fma_f32 v24, v33, v88, v35
	v_and_b32_e32 v32, 0xffff0000, v64
	v_and_b32_e32 v33, 0xffff0000, v66
	v_mul_f32_e32 v34, v33, v91
	v_mul_f32_e32 v35, v32, v91
	v_fma_f32 v19, v32, v90, -v34
	v_fma_f32 v25, v33, v90, v35
	v_lshlrev_b32_e32 v32, 16, v65
	v_lshlrev_b32_e32 v33, 16, v67
	v_mul_f32_e32 v34, v33, v93
	v_mul_f32_e32 v35, v32, v93
	v_fma_f32 v20, v32, v92, -v34
	v_fma_f32 v22, v33, v92, v35
	v_and_b32_e32 v32, 0xffff0000, v65
	v_and_b32_e32 v33, 0xffff0000, v67
	v_mul_f32_e32 v34, v33, v95
	v_mul_f32_e32 v35, v32, v95
	v_fma_f32 v21, v32, v94, -v34
	v_fma_f32 v23, v33, v94, v35
	v_lshlrev_b32_e32 v32, 16, v68
	v_lshlrev_b32_e32 v33, 16, v70
	v_mul_f32_e32 v34, v33, v97
	v_mul_f32_e32 v35, v32, v97
	v_fma_f32 v16, v32, v96, -v34
	v_fma_f32 v30, v33, v96, v35
	v_and_b32_e32 v32, 0xffff0000, v68
	v_and_b32_e32 v33, 0xffff0000, v70
	v_mul_f32_e32 v34, v33, v99
	v_mul_f32_e32 v35, v32, v99
	v_fma_f32 v17, v32, v98, -v34
	v_fma_f32 v31, v33, v98, v35
	v_lshlrev_b32_e32 v32, 16, v69
	v_lshlrev_b32_e32 v33, 16, v71
	v_mul_f32_e32 v34, v33, v101
	v_mul_f32_e32 v35, v32, v101
	v_fma_f32 v26, v32, v100, -v34
	v_fma_f32 v28, v33, v100, v35
	v_and_b32_e32 v32, 0xffff0000, v69
	v_and_b32_e32 v33, 0xffff0000, v71
	v_mul_f32_e32 v34, v33, v103
	v_mul_f32_e32 v35, v32, v103
	v_fma_f32 v27, v32, v102, -v34
	v_fma_f32 v29, v33, v102, v35
	s_branch .Lkv_done_b

.Lkv_done_b:
	s_branch .LBB0_390
.LBB0_537:
	v_add_u32_e32 v190, s29, v181
	v_cmp_le_i32_e64 s[0:1], s3, v190
	v_cmp_gt_i32_e64 s[72:73], s28, v190
	s_and_b64 s[28:29], s[0:1], s[72:73]
	v_mov_b32_e32 v189, 0
	v_mov_b32_e32 v188, 0
	v_mov_b32_e32 v187, 0
	v_mov_b32_e32 v186, 0
	v_mov_b32_e32 v73, 0
	v_mov_b32_e32 v72, 0
	v_mov_b32_e32 v65, 0
	v_mov_b32_e32 v64, 0
	s_and_saveexec_b64 s[0:1], s[28:29]
	s_cbranch_execz .LBB0_539
	v_mov_b64_e32 v[64:65], s[20:21]
	v_mad_i64_i32 v[64:65], s[28:29], v190, s92, v[64:65]
	v_lshlrev_b32_e32 v200, 1, v102
	v_mad_i64_i32 v[18:19], s[28:29], v190, s92, v[18:19]
	v_lshl_add_u64 v[64:65], v[64:65], 0, v[200:201]
	global_load_dwordx2 v[18:19], v[18:19], off
	s_nop 0
	global_load_dwordx2 v[188:189], v[64:65], off offset:512
	s_waitcnt vmcnt(1)
	v_lshlrev_b32_e32 v64, 16, v18
	v_and_b32_e32 v65, 0xffff0000, v18
	v_lshlrev_b32_e32 v72, 16, v19
	v_and_b32_e32 v73, 0xffff0000, v19
	s_waitcnt vmcnt(0)
	v_lshlrev_b32_e32 v186, 16, v188
	v_and_b32_e32 v187, 0xffff0000, v188
	v_lshlrev_b32_e32 v188, 16, v189
	v_and_b32_e32 v189, 0xffff0000, v189
